# LayerNorm reductions (LN1/LN2): butterfly via DPP row_ror + permlane swaps instead of ds_bpermute (bit-identical)
# speedup vs baseline: 1.0133x; 1.0013x over previous
; DI int TIDX() { int t = __builtin_amdgcn_workitem_id_x(); asm volatile("" : "+v"(t)); return t; }
; template <int GRP>
; DI void ln_items(float* X, const float* gam, const float* bet, bf16_t* u2, const float* sc, const float* sh, int item0) {
;   const int tid = TIDX(), lane = tid & 63, wave = tid >> 6;
;   f32x4 v[GRP][4];
; #pragma unroll
;   for (int g = 0; g < GRP; ++g) {
;     const size_t tok = (size_t)(item0 + g) * 4 + wave;
; #pragma unroll
;     for (int j = 0; j < 4; ++j) v[g][j] = *(const f32x4*)(X + tok * 1024 + j * 256 + lane * 4);
;   }
; #pragma unroll
;   for (int g = 0; g < GRP; ++g) {
;     const size_t tok = (size_t)(item0 + g) * 4 + wave;
;     const int b = (int)(tok >> 13);
;     float s = 0.f;
; #pragma unroll
;     for (int j = 0; j < 4; ++j) s += v[g][j][0] + v[g][j][1] + v[g][j][2] + v[g][j][3];
; #pragma unroll
;     for (int off = 32; off >= 1; off >>= 1) s += __shfl_xor(s, off);
;     const float mu = s * (1.f / 1024.f);
.LBB0_156:
	s_nop 0
	v_mov_b32_e32 v2, v218
	s_add_i32 s14, s16, s9
	v_ashrrev_i32_e32 v0, 6, v2
	v_ashrrev_i32_e32 v1, 31, v0
	s_add_i32 s0, s14, 4
	v_lshlrev_b64 v[72:73], 12, v[0:1]
	v_lshlrev_b32_e32 v2, 4, v2
	v_lshl_add_u64 v[0:1], s[68:69], 0, v[72:73]
	v_and_b32_e32 v192, 0x3f0, v2
	s_ashr_i32 s1, s0, 31
	v_lshl_add_u64 v[0:1], v[0:1], 0, v[192:193]
	s_lshl_b64 s[6:7], s[0:1], 14
	v_lshl_add_u64 v[2:3], v[0:1], 0, s[6:7]
	global_load_dwordx4 v[68:71], v[2:3], off
	global_load_dwordx4 v[64:67], v[2:3], off offset:1024
	global_load_dwordx4 v[60:63], v[2:3], off offset:2048
	global_load_dwordx4 v[56:59], v[2:3], off offset:3072
	s_add_i32 s0, s14, 5
	s_ashr_i32 s1, s0, 31
	s_lshl_b64 s[0:1], s[0:1], 14
	v_lshl_add_u64 v[2:3], v[0:1], 0, s[0:1]
	global_load_dwordx4 v[52:55], v[2:3], off
	global_load_dwordx4 v[48:51], v[2:3], off offset:1024
	global_load_dwordx4 v[44:47], v[2:3], off offset:2048
	global_load_dwordx4 v[40:43], v[2:3], off offset:3072
	v_and_b32_e32 v32, 64, v223
	v_add_u32_e32 v36, 64, v32
	s_add_i32 s10, s14, 6
	s_ashr_i32 s11, s10, 31
	s_lshl_b64 s[12:13], s[10:11], 14
	s_add_i32 s10, s14, 7
	s_ashr_i32 s11, s10, 31
	s_lshl_b64 s[10:11], s[10:11], 14
	s_add_u32 s6, s68, s6
	s_addc_u32 s7, s69, s7
	v_lshl_add_u64 v[74:75], s[6:7], 0, v[72:73]
	v_lshl_add_u64 v[2:3], v[0:1], 0, s[12:13]
	v_lshl_add_u64 v[0:1], v[0:1], 0, s[10:11]
	global_load_dwordx4 v[28:31], v[2:3], off
	global_load_dwordx4 v[24:27], v[2:3], off offset:1024
	global_load_dwordx4 v[20:23], v[2:3], off offset:2048
	global_load_dwordx4 v[16:19], v[2:3], off offset:3072
	global_load_dwordx4 v[12:15], v[0:1], off
	global_load_dwordx4 v[8:11], v[0:1], off offset:1024
	global_load_dwordx4 v[4:7], v[0:1], off offset:2048
	s_nop 0
	global_load_dwordx4 v[0:3], v[0:1], off offset:3072
	s_add_u32 s0, s68, s0
	s_addc_u32 s1, s69, s1
	v_lshl_add_u64 v[92:93], s[0:1], 0, v[72:73]
	s_mov_b32 s0, 0x3727c5ac
	s_waitcnt vmcnt(15)
	v_mov_b32_e32 v32, v68
	s_waitcnt vmcnt(14)
	v_mov_b32_e32 v33, v64
	v_mov_b32_e32 v34, v69
	v_mov_b32_e32 v35, v65
	v_pk_add_f32 v[32:33], v[32:33], v[34:35]
	v_mov_b32_e32 v34, v70
	v_mov_b32_e32 v35, v66
	v_pk_add_f32 v[32:33], v[34:35], v[32:33]
	v_mov_b32_e32 v34, v71
	v_mov_b32_e32 v35, v67
	v_pk_add_f32 v[32:33], v[34:35], v[32:33]
	s_waitcnt vmcnt(13)
	v_mov_b32_e32 v34, v61
	v_add_f32_e32 v32, 0, v32
	v_add_f32_e32 v37, v32, v33
	v_mov_b32_e32 v32, v60
	s_waitcnt vmcnt(12)
	v_mov_b32_e32 v33, v56
	v_mov_b32_e32 v35, v57
	v_pk_add_f32 v[32:33], v[32:33], v[34:35]
	v_mov_b32_e32 v34, v62
	v_mov_b32_e32 v35, v58
	v_pk_add_f32 v[32:33], v[34:35], v[32:33]
	v_mov_b32_e32 v34, v63
	v_mov_b32_e32 v35, v59
	v_pk_add_f32 v[32:33], v[34:35], v[32:33]
	s_nop 0
	v_add_f32_e32 v32, v37, v32
	v_add_f32_e32 v32, v32, v33
	v_xor_b32_e32 v33, 32, v223
	v_cmp_lt_i32_e32 vcc, v33, v36
	s_nop 1
	v_cndmask_b32_e32 v33, v223, v33, vcc
	v_lshlrev_b32_e32 v82, 2, v33
	v_mov_b32_e32 v33, v32
	s_nop 1
	v_permlane32_swap_b32_e32 v33, v32
	s_waitcnt lgkmcnt(0)
	v_add_f32_e32 v32, v32, v33
	v_xor_b32_e32 v33, 16, v223
	v_cmp_lt_i32_e32 vcc, v33, v36
	s_nop 1
	v_cndmask_b32_e32 v33, v223, v33, vcc
	v_lshlrev_b32_e32 v83, 2, v33
	v_mov_b32_e32 v33, v32
	s_nop 1
	v_permlane16_swap_b32_e32 v33, v32
	s_waitcnt lgkmcnt(0)
	v_add_f32_e32 v32, v32, v33
	v_xor_b32_e32 v33, 8, v223
	v_cmp_lt_i32_e32 vcc, v33, v36
	s_nop 1
	v_cndmask_b32_e32 v33, v223, v33, vcc
	v_lshlrev_b32_e32 v84, 2, v33
	s_nop 1
	v_mov_b32_dpp v33, v32 row_ror:8 row_mask:0xf bank_mask:0xf
	s_waitcnt lgkmcnt(0)
	v_add_f32_e32 v32, v32, v33
	v_xor_b32_e32 v33, 4, v223
	v_cmp_lt_i32_e32 vcc, v33, v36
	s_nop 1
	v_cndmask_b32_e32 v33, v223, v33, vcc
	v_lshlrev_b32_e32 v85, 2, v33
	s_nop 1
	v_mov_b32_dpp v33, v32 row_ror:4 row_mask:0xf bank_mask:0xf
	s_waitcnt lgkmcnt(0)
	v_add_f32_e32 v32, v32, v33
	v_xor_b32_e32 v33, 2, v223
	v_cmp_lt_i32_e32 vcc, v33, v36
	s_nop 1
	v_cndmask_b32_e32 v33, v223, v33, vcc
	v_lshlrev_b32_e32 v86, 2, v33
	s_nop 1
	v_mov_b32_dpp v33, v32 row_ror:2 row_mask:0xf bank_mask:0xf
	s_waitcnt lgkmcnt(0)
	v_add_f32_e32 v32, v32, v33
	v_xor_b32_e32 v33, 1, v223
	v_cmp_lt_i32_e32 vcc, v33, v36
	s_nop 1
	v_cndmask_b32_e32 v33, v223, v33, vcc
	v_lshlrev_b32_e32 v87, 2, v33
	s_nop 1
	v_mov_b32_dpp v33, v32 row_ror:1 row_mask:0xf bank_mask:0xf
	s_waitcnt lgkmcnt(0)
	v_add_f32_e32 v32, v32, v33
	v_mul_f32_e32 v80, 0x3a800000, v32
	v_pk_add_f32 v[76:77], v[68:69], v[80:81] op_sel_hi:[1,0] neg_lo:[0,1] neg_hi:[0,1]
	v_pk_add_f32 v[78:79], v[70:71], v[80:81] op_sel_hi:[1,0] neg_lo:[0,1] neg_hi:[0,1]
	v_lshl_add_u64 v[68:69], v[74:75], 0, v[192:193]
	v_pk_add_f32 v[70:71], v[64:65], v[80:81] op_sel_hi:[1,0] neg_lo:[0,1] neg_hi:[0,1]
	v_pk_add_f32 v[74:75], v[66:67], v[80:81] op_sel_hi:[1,0] neg_lo:[0,1] neg_hi:[0,1]
	v_pk_add_f32 v[64:65], v[60:61], v[80:81] op_sel_hi:[1,0] neg_lo:[0,1] neg_hi:[0,1]
	v_pk_add_f32 v[66:67], v[62:63], v[80:81] op_sel_hi:[1,0] neg_lo:[0,1] neg_hi:[0,1]
	v_pk_add_f32 v[60:61], v[56:57], v[80:81] op_sel_hi:[1,0] neg_lo:[0,1] neg_hi:[0,1]
	v_pk_add_f32 v[62:63], v[58:59], v[80:81] op_sel_hi:[1,0] neg_lo:[0,1] neg_hi:[0,1]
	s_waitcnt vmcnt(11)
	v_mov_b32_e32 v56, v52
	s_waitcnt vmcnt(10)
	v_mov_b32_e32 v57, v48
	v_mov_b32_e32 v58, v53
	v_mov_b32_e32 v59, v49
	v_pk_add_f32 v[56:57], v[56:57], v[58:59]
	v_mov_b32_e32 v58, v54
	v_mov_b32_e32 v59, v50
	v_pk_add_f32 v[56:57], v[58:59], v[56:57]
	v_mov_b32_e32 v58, v55
	v_mov_b32_e32 v59, v51
	v_pk_add_f32 v[56:57], v[58:59], v[56:57]
	s_waitcnt vmcnt(9)
	v_mov_b32_e32 v58, v45
	v_add_f32_e32 v56, 0, v56
	v_add_f32_e32 v90, v56, v57
	v_mov_b32_e32 v56, v44
	s_waitcnt vmcnt(8)
; template <int GRP>
; DI void ln_items(float* X, const float* gam, const float* bet, bf16_t* u2, const float* sc, const float* sh, int item0) {
;     ...
; #pragma unroll
;     for (int j = 0; j < 4; ++j) s += v[g][j][0] + v[g][j][1] + v[g][j][2] + v[g][j][3];
; #pragma unroll
;     for (int off = 32; off >= 1; off >>= 1) s += __shfl_xor(s, off);
;     const float mu = s * (1.f / 1024.f);
;     float q = 0.f;
; #pragma unroll
;     for (int j = 0; j < 4; ++j)
; #pragma unroll
;       for (int e = 0; e < 4; ++e) { const float d = v[g][j][e] - mu; q += d * d; }
; #pragma unroll
;     for (int off = 32; off >= 1; off >>= 1) q += __shfl_xor(q, off);
;     const float rstd = rsqrtf(q * (1.f / 1024.f) + 1e-5f);
	v_mov_b32_e32 v57, v40
	v_mov_b32_e32 v59, v41
	v_pk_add_f32 v[56:57], v[56:57], v[58:59]
	v_mov_b32_e32 v58, v46
	v_mov_b32_e32 v59, v42
	v_pk_add_f32 v[56:57], v[58:59], v[56:57]
	v_mov_b32_e32 v58, v47
	v_mov_b32_e32 v59, v43
	v_pk_add_f32 v[56:57], v[58:59], v[56:57]
	global_load_dwordx4 v[32:35], v192, s[22:23]
	global_load_dwordx4 v[36:39], v192, s[24:25]
	v_add_f32_e32 v56, v90, v56
	v_add_f32_e32 v56, v56, v57
	v_mov_b32_e32 v57, v56
	s_nop 1
	v_permlane32_swap_b32_e32 v57, v56
	v_mov_b32_e32 v59, v77
	v_mov_b32_e32 v97, v78
	v_pk_mul_f32 v[88:89], v[60:61], v[60:61]
	v_pk_mul_f32 v[80:81], v[62:63], v[62:63]
	s_waitcnt lgkmcnt(0)
	v_add_f32_e32 v56, v56, v57
	v_mov_b32_e32 v57, v56
	s_nop 1
	v_permlane16_swap_b32_e32 v57, v56
	s_waitcnt lgkmcnt(0)
	v_add_f32_e32 v56, v56, v57
	s_nop 1
	v_mov_b32_dpp v57, v56 row_ror:8 row_mask:0xf bank_mask:0xf
	s_waitcnt lgkmcnt(0)
	v_add_f32_e32 v56, v56, v57
	s_nop 1
	v_mov_b32_dpp v57, v56 row_ror:4 row_mask:0xf bank_mask:0xf
	s_waitcnt lgkmcnt(0)
	v_add_f32_e32 v56, v56, v57
	s_nop 1
	v_mov_b32_dpp v57, v56 row_ror:2 row_mask:0xf bank_mask:0xf
	s_waitcnt lgkmcnt(0)
	v_add_f32_e32 v56, v56, v57
	s_nop 1
	v_mov_b32_dpp v57, v56 row_ror:1 row_mask:0xf bank_mask:0xf
	s_waitcnt lgkmcnt(0)
	v_add_f32_e32 v56, v56, v57
	v_mul_f32_e32 v90, 0x3a800000, v56
	v_pk_add_f32 v[56:57], v[52:53], v[90:91] op_sel_hi:[1,0] neg_lo:[0,1] neg_hi:[0,1]
	v_mov_b32_e32 v53, v76
	v_mov_b32_e32 v58, v57
	v_mov_b32_e32 v52, v56
	v_pk_mul_f32 v[58:59], v[58:59], v[58:59]
	v_pk_add_f32 v[50:51], v[50:51], v[90:91] op_sel_hi:[1,0] neg_lo:[0,1] neg_hi:[0,1]
	v_pk_fma_f32 v[94:95], v[52:53], v[52:53], v[58:59]
	v_pk_add_f32 v[58:59], v[54:55], v[90:91] op_sel_hi:[1,0] neg_lo:[0,1] neg_hi:[0,1]
	v_lshl_add_u64 v[52:53], v[92:93], 0, v[192:193]
	v_mov_b32_e32 v96, v58
	v_pk_add_f32 v[54:55], v[48:49], v[90:91] op_sel_hi:[1,0] neg_lo:[0,1] neg_hi:[0,1]
	v_mov_b32_e32 v92, v59
	v_mov_b32_e32 v93, v79
	v_pk_fma_f32 v[94:95], v[96:97], v[96:97], v[94:95]
	v_mov_b32_e32 v96, v55
	v_pk_fma_f32 v[92:93], v[92:93], v[92:93], v[94:95]
	v_mov_b32_e32 v94, v54
	v_mov_b32_e32 v95, v70
	v_mov_b32_e32 v97, v71
	v_pk_fma_f32 v[92:93], v[94:95], v[94:95], v[92:93]
	v_mov_b32_e32 v94, v50
	v_pk_fma_f32 v[92:93], v[96:97], v[96:97], v[92:93]
	v_mov_b32_e32 v95, v74
	v_pk_add_f32 v[48:49], v[44:45], v[90:91] op_sel_hi:[1,0] neg_lo:[0,1] neg_hi:[0,1]
	v_mov_b32_e32 v96, v51
	v_mov_b32_e32 v97, v75
	v_pk_fma_f32 v[92:93], v[94:95], v[94:95], v[92:93]
	v_mov_b32_e32 v94, v48
	v_pk_fma_f32 v[92:93], v[96:97], v[96:97], v[92:93]
	v_mov_b32_e32 v95, v64
	v_pk_add_f32 v[46:47], v[46:47], v[90:91] op_sel_hi:[1,0] neg_lo:[0,1] neg_hi:[0,1]
	v_mov_b32_e32 v96, v49
	v_mov_b32_e32 v97, v65
	v_pk_fma_f32 v[92:93], v[94:95], v[94:95], v[92:93]
	v_pk_add_f32 v[44:45], v[40:41], v[90:91] op_sel_hi:[1,0] neg_lo:[0,1] neg_hi:[0,1]
	v_pk_fma_f32 v[92:93], v[96:97], v[96:97], v[92:93]
	v_mov_b32_e32 v94, v46
	v_mov_b32_e32 v95, v66
	v_pk_mul_f32 v[40:41], v[44:45], v[44:45]
	v_mov_b32_e32 v96, v47
	v_mov_b32_e32 v97, v67
	v_pk_fma_f32 v[92:93], v[94:95], v[94:95], v[92:93]
	v_mov_b32_e32 v94, v40
	v_pk_fma_f32 v[92:93], v[96:97], v[96:97], v[92:93]
	v_mov_b32_e32 v95, v88
	v_pk_add_f32 v[42:43], v[42:43], v[90:91] op_sel_hi:[1,0] neg_lo:[0,1] neg_hi:[0,1]
	v_pk_add_f32 v[92:93], v[94:95], v[92:93]
	v_pk_mul_f32 v[90:91], v[42:43], v[42:43]
	v_mov_b32_e32 v88, v41
	v_pk_add_f32 v[40:41], v[88:89], v[92:93]
	v_mov_b32_e32 v88, v90
	v_mov_b32_e32 v89, v80
	v_pk_add_f32 v[40:41], v[88:89], v[40:41]
	v_mov_b32_e32 v80, v91
	v_pk_add_f32 v[40:41], v[80:81], v[40:41]
	v_mov_b32_e32 v81, v41
	s_nop 1
	v_permlane32_swap_b32_e32 v81, v41
	v_mov_b32_e32 v80, v40
	s_nop 1
	v_permlane32_swap_b32_e32 v80, v40
	s_waitcnt lgkmcnt(0)
	v_pk_add_f32 v[40:41], v[40:41], v[80:81]
	v_mov_b32_e32 v81, v41
	s_nop 1
	v_permlane16_swap_b32_e32 v81, v41
	v_mov_b32_e32 v80, v40
	s_nop 1
	v_permlane16_swap_b32_e32 v80, v40
	s_waitcnt lgkmcnt(0)
	v_pk_add_f32 v[40:41], v[40:41], v[80:81]
	s_nop 1
	v_mov_b32_dpp v81, v41 row_ror:8 row_mask:0xf bank_mask:0xf
	s_nop 1
	v_mov_b32_dpp v80, v40 row_ror:8 row_mask:0xf bank_mask:0xf
	s_waitcnt lgkmcnt(0)
	v_pk_add_f32 v[40:41], v[40:41], v[80:81]
	s_nop 1
	v_mov_b32_dpp v81, v41 row_ror:4 row_mask:0xf bank_mask:0xf
	s_nop 1
	v_mov_b32_dpp v80, v40 row_ror:4 row_mask:0xf bank_mask:0xf
	s_waitcnt lgkmcnt(0)
	v_pk_add_f32 v[40:41], v[40:41], v[80:81]
	s_nop 1
	v_mov_b32_dpp v81, v41 row_ror:2 row_mask:0xf bank_mask:0xf
	s_nop 1
	v_mov_b32_dpp v80, v40 row_ror:2 row_mask:0xf bank_mask:0xf
	s_waitcnt lgkmcnt(0)
	v_pk_add_f32 v[40:41], v[40:41], v[80:81]
	s_nop 1
	v_mov_b32_dpp v81, v41 row_ror:1 row_mask:0xf bank_mask:0xf
	s_nop 1
	v_mov_b32_dpp v80, v40 row_ror:1 row_mask:0xf bank_mask:0xf
	s_waitcnt lgkmcnt(0)
	v_pk_add_f32 v[80:81], v[40:41], v[80:81]
	v_mov_b64_e32 v[40:41], s[0:1]
	v_pk_fma_f32 v[80:81], v[80:81], s[18:19], v[40:41] op_sel_hi:[1,0,0]
	s_nop 0
	v_mul_f32_e32 v88, 0x4b800000, v81
	v_cmp_gt_f32_e64 s[0:1], s39, v81
	v_cmp_gt_f32_e32 vcc, s39, v80
	s_nop 0
	v_cndmask_b32_e64 v81, v81, v88, s[0:1]
	v_rsq_f32_e32 v81, v81
	s_nop 0
	v_mul_f32_e32 v88, 0x45800000, v81
	v_cndmask_b32_e64 v88, v81, v88, s[0:1]
	v_pk_mul_f32 v[76:77], v[76:77], v[88:89] op_sel_hi:[1,0]
	v_pk_mul_f32 v[78:79], v[78:79], v[88:89] op_sel_hi:[1,0]
	s_waitcnt vmcnt(0)
; template <int GRP>
; DI void ln_items(float* X, const float* gam, const float* bet, bf16_t* u2, const float* sc, const float* sh, int item0) {
;     ...
;   for (int g = 0; g < GRP; ++g) {
;     const size_t tok = (size_t)(item0 + g) * 4 + wave;
;     const int b = (int)(tok >> 13);
;     float s = 0.f;
; #pragma unroll
;     for (int j = 0; j < 4; ++j) s += v[g][j][0] + v[g][j][1] + v[g][j][2] + v[g][j][3];
; #pragma unroll
;     for (int off = 32; off >= 1; off >>= 1) s += __shfl_xor(s, off);
;     const float mu = s * (1.f / 1024.f);
;     float q = 0.f;
; #pragma unroll
;     for (int j = 0; j < 4; ++j)
; #pragma unroll
;       for (int e = 0; e < 4; ++e) { const float d = v[g][j][e] - mu; q += d * d; }
; #pragma unroll
;     for (int off = 32; off >= 1; off >>= 1) q += __shfl_xor(q, off);
;     const float rstd = rsqrtf(q * (1.f / 1024.f) + 1e-5f);
; #pragma unroll
;     for (int j = 0; j < 4; ++j) {
;       const int col = j * 256 + lane * 4;
;       const f32x4 gg = *(const f32x4*)(gam + col), be = *(const f32x4*)(bet + col);
;       f32x4 y;
; #pragma unroll
;       for (int e = 0; e < 4; ++e) y[e] = (v[g][j][e] - mu) * rstd * gg[e] + be[e];
;       *(f32x4*)(X + tok * 1024 + col) = y;
	v_pk_fma_f32 v[32:33], v[32:33], v[76:77], v[36:37]
	v_pk_fma_f32 v[34:35], v[34:35], v[78:79], v[38:39]
	global_store_dwordx4 v[68:69], v[32:35], off
	global_load_dwordx4 v[32:35], v192, s[22:23] offset:1024
	s_nop 0
	global_load_dwordx4 v[36:39], v192, s[24:25] offset:1024
	v_pk_mul_f32 v[74:75], v[74:75], v[88:89] op_sel_hi:[1,0]
	v_pk_mul_f32 v[70:71], v[70:71], v[88:89] op_sel_hi:[1,0]
	v_pk_mul_f32 v[66:67], v[66:67], v[88:89] op_sel_hi:[1,0]
	v_pk_mul_f32 v[64:65], v[64:65], v[88:89] op_sel_hi:[1,0]
	v_pk_mul_f32 v[62:63], v[62:63], v[88:89] op_sel_hi:[1,0]
	v_pk_mul_f32 v[60:61], v[60:61], v[88:89] op_sel_hi:[1,0]
	s_add_u32 s0, s68, s12
	s_addc_u32 s1, s69, s13
	s_waitcnt vmcnt(0)
	v_pk_fma_f32 v[32:33], v[32:33], v[70:71], v[36:37]
	v_pk_fma_f32 v[34:35], v[34:35], v[74:75], v[38:39]
	global_store_dwordx4 v[68:69], v[32:35], off offset:1024
	global_load_dwordx4 v[32:35], v192, s[22:23] offset:2048
	s_nop 0
	global_load_dwordx4 v[36:39], v192, s[24:25] offset:2048
	s_waitcnt vmcnt(0)
	v_pk_fma_f32 v[32:33], v[32:33], v[64:65], v[36:37]
	v_pk_fma_f32 v[34:35], v[34:35], v[66:67], v[38:39]
	global_store_dwordx4 v[68:69], v[32:35], off offset:2048
	global_load_dwordx4 v[32:35], v192, s[22:23] offset:3072
	s_nop 0
	global_load_dwordx4 v[36:39], v192, s[24:25] offset:3072
	s_waitcnt vmcnt(0)
	v_pk_fma_f32 v[32:33], v[32:33], v[60:61], v[36:37]
	v_pk_fma_f32 v[34:35], v[34:35], v[62:63], v[38:39]
	global_store_dwordx4 v[68:69], v[32:35], off offset:3072
	global_load_dwordx4 v[32:35], v192, s[22:23]
	s_nop 0
	global_load_dwordx4 v[36:39], v192, s[24:25]
	v_mul_f32_e32 v60, 0x4b800000, v80
	v_cndmask_b32_e32 v60, v80, v60, vcc
	v_rsq_f32_e32 v60, v60
	s_nop 0
	v_mul_f32_e32 v61, 0x45800000, v60
	v_cndmask_b32_e32 v60, v60, v61, vcc
	v_pk_mul_f32 v[58:59], v[58:59], v[60:61] op_sel_hi:[1,0]
	v_pk_mul_f32 v[56:57], v[56:57], v[60:61] op_sel_hi:[1,0]
	v_pk_mul_f32 v[50:51], v[50:51], v[60:61] op_sel_hi:[1,0]
	v_pk_mul_f32 v[54:55], v[54:55], v[60:61] op_sel_hi:[1,0]
	v_pk_mul_f32 v[46:47], v[46:47], v[60:61] op_sel_hi:[1,0]
	v_pk_mul_f32 v[48:49], v[48:49], v[60:61] op_sel_hi:[1,0]
	v_pk_mul_f32 v[42:43], v[42:43], v[60:61] op_sel_hi:[1,0]
	v_pk_mul_f32 v[44:45], v[44:45], v[60:61] op_sel_hi:[1,0]
	s_waitcnt vmcnt(0)
	v_pk_fma_f32 v[32:33], v[32:33], v[56:57], v[36:37]
	v_pk_fma_f32 v[34:35], v[34:35], v[58:59], v[38:39]
	global_store_dwordx4 v[52:53], v[32:35], off
	global_load_dwordx4 v[32:35], v192, s[22:23] offset:1024
	s_nop 0
	global_load_dwordx4 v[36:39], v192, s[24:25] offset:1024
	s_waitcnt vmcnt(0)
	v_pk_fma_f32 v[32:33], v[32:33], v[54:55], v[36:37]
	v_pk_fma_f32 v[34:35], v[34:35], v[50:51], v[38:39]
	global_store_dwordx4 v[52:53], v[32:35], off offset:1024
	global_load_dwordx4 v[32:35], v192, s[22:23] offset:2048
	s_nop 0
	global_load_dwordx4 v[36:39], v192, s[24:25] offset:2048
	v_mov_b32_e32 v50, v13
	v_mov_b32_e32 v51, v9
	s_waitcnt vmcnt(0)
	v_pk_fma_f32 v[32:33], v[32:33], v[48:49], v[36:37]
	v_pk_fma_f32 v[34:35], v[34:35], v[46:47], v[38:39]
	global_store_dwordx4 v[52:53], v[32:35], off offset:2048
	global_load_dwordx4 v[32:35], v192, s[22:23] offset:3072
	s_nop 0
	global_load_dwordx4 v[36:39], v192, s[24:25] offset:3072
	v_mov_b32_e32 v48, v12
	v_mov_b32_e32 v49, v8
	v_pk_add_f32 v[48:49], v[48:49], v[50:51]
	v_mov_b32_e32 v50, v14
	v_mov_b32_e32 v51, v10
	v_pk_add_f32 v[48:49], v[50:51], v[48:49]
	v_mov_b32_e32 v50, v15
	v_mov_b32_e32 v51, v11
	v_pk_add_f32 v[48:49], v[50:51], v[48:49]
	v_mov_b32_e32 v50, v5
	v_add_f32_e32 v48, 0, v48
	v_mov_b32_e32 v51, v1
	v_lshl_add_u64 v[46:47], s[0:1], 0, v[72:73]
	s_add_u32 s0, s68, s10
	s_addc_u32 s1, s69, s11
	s_add_i32 s9, s9, 4
	s_cmp_gt_u32 s9, 27
	s_waitcnt vmcnt(0)
	v_pk_fma_f32 v[32:33], v[32:33], v[44:45], v[36:37]
	v_pk_fma_f32 v[34:35], v[34:35], v[42:43], v[38:39]
	global_store_dwordx4 v[52:53], v[32:35], off offset:3072
	v_add_f32_e32 v52, v48, v49
	v_mov_b32_e32 v48, v4
	v_mov_b32_e32 v32, v28
	v_mov_b32_e32 v33, v24
	v_mov_b32_e32 v34, v29
	v_mov_b32_e32 v35, v25
	v_pk_add_f32 v[32:33], v[32:33], v[34:35]
	v_mov_b32_e32 v34, v30
	v_mov_b32_e32 v35, v26
	v_pk_add_f32 v[32:33], v[34:35], v[32:33]
	v_mov_b32_e32 v34, v31
	v_mov_b32_e32 v35, v27
	v_pk_add_f32 v[32:33], v[34:35], v[32:33]
	v_mov_b32_e32 v34, v21
	v_add_f32_e32 v32, 0, v32
	v_add_f32_e32 v36, v32, v33
	v_mov_b32_e32 v32, v20
	v_mov_b32_e32 v33, v16
	v_mov_b32_e32 v35, v17
	v_pk_add_f32 v[32:33], v[32:33], v[34:35]
	v_mov_b32_e32 v34, v22
	v_mov_b32_e32 v35, v18
	v_pk_add_f32 v[32:33], v[34:35], v[32:33]
	v_mov_b32_e32 v34, v23
	v_mov_b32_e32 v35, v19
	v_pk_add_f32 v[32:33], v[34:35], v[32:33]
	v_mov_b32_e32 v49, v0
	v_add_f32_e32 v32, v36, v32
	v_add_f32_e32 v32, v32, v33
	v_mov_b32_e32 v33, v32
	s_nop 1
	v_permlane32_swap_b32_e32 v33, v32
	v_pk_add_f32 v[48:49], v[48:49], v[50:51]
	v_mov_b32_e32 v50, v6
	v_mov_b32_e32 v51, v2
	v_pk_add_f32 v[48:49], v[50:51], v[48:49]
	s_waitcnt lgkmcnt(0)
	v_add_f32_e32 v32, v32, v33
	v_mov_b32_e32 v33, v32
	s_nop 1
	v_permlane16_swap_b32_e32 v33, v32
	v_mov_b32_e32 v50, v7
	v_mov_b32_e32 v51, v3
	v_pk_add_f32 v[48:49], v[50:51], v[48:49]
	v_lshl_add_u64 v[50:51], s[0:1], 0, v[72:73]
	s_waitcnt lgkmcnt(0)
	v_add_f32_e32 v32, v32, v33
	s_nop 1
	v_mov_b32_dpp v33, v32 row_ror:8 row_mask:0xf bank_mask:0xf
	v_add_f32_e32 v48, v52, v48
	v_add_f32_e32 v48, v48, v49
	v_mov_b32_e32 v49, v48
	s_nop 1
	v_permlane32_swap_b32_e32 v49, v48
	s_waitcnt lgkmcnt(0)
	v_add_f32_e32 v32, v32, v33
	s_nop 1
	v_mov_b32_dpp v33, v32 row_ror:4 row_mask:0xf bank_mask:0xf
	s_waitcnt lgkmcnt(0)
	v_add_f32_e32 v48, v48, v49
	v_mov_b32_e32 v49, v48
	s_nop 1
	v_permlane16_swap_b32_e32 v49, v48
	s_waitcnt lgkmcnt(0)
; template <int GRP>
; DI void ln_items(float* X, const float* gam, const float* bet, bf16_t* u2, const float* sc, const float* sh, int item0) {
;     ...
; #pragma unroll
;     for (int j = 0; j < 4; ++j) s += v[g][j][0] + v[g][j][1] + v[g][j][2] + v[g][j][3];
; #pragma unroll
;     for (int off = 32; off >= 1; off >>= 1) s += __shfl_xor(s, off);
;     const float mu = s * (1.f / 1024.f);
;     float q = 0.f;
; #pragma unroll
;     for (int j = 0; j < 4; ++j)
; #pragma unroll
;       for (int e = 0; e < 4; ++e) { const float d = v[g][j][e] - mu; q += d * d; }
; #pragma unroll
;     for (int off = 32; off >= 1; off >>= 1) q += __shfl_xor(q, off);
;     const float rstd = rsqrtf(q * (1.f / 1024.f) + 1e-5f);
	v_add_f32_e32 v32, v32, v33
	s_nop 1
	v_mov_b32_dpp v33, v32 row_ror:2 row_mask:0xf bank_mask:0xf
	s_waitcnt lgkmcnt(0)
	v_add_f32_e32 v48, v48, v49
	s_nop 1
	v_mov_b32_dpp v49, v48 row_ror:8 row_mask:0xf bank_mask:0xf
	s_waitcnt lgkmcnt(0)
	v_add_f32_e32 v32, v32, v33
	s_nop 1
	v_mov_b32_dpp v33, v32 row_ror:1 row_mask:0xf bank_mask:0xf
	s_waitcnt lgkmcnt(0)
	v_add_f32_e32 v48, v48, v49
	s_nop 1
	v_mov_b32_dpp v49, v48 row_ror:4 row_mask:0xf bank_mask:0xf
	s_waitcnt lgkmcnt(0)
	v_add_f32_e32 v32, v32, v33
	v_mul_f32_e32 v44, 0x3a800000, v32
	global_load_dwordx4 v[32:35], v192, s[22:23]
	global_load_dwordx4 v[36:39], v192, s[24:25]
	s_waitcnt lgkmcnt(0)
	v_add_f32_e32 v48, v48, v49
	s_nop 1
	v_mov_b32_dpp v49, v48 row_ror:2 row_mask:0xf bank_mask:0xf
	v_pk_add_f32 v[42:43], v[28:29], v[44:45] op_sel_hi:[1,0] neg_lo:[0,1] neg_hi:[0,1]
	v_pk_add_f32 v[30:31], v[30:31], v[44:45] op_sel_hi:[1,0] neg_lo:[0,1] neg_hi:[0,1]
	v_mov_b32_e32 v55, v43
	v_mov_b32_e32 v57, v30
	s_waitcnt lgkmcnt(0)
	v_add_f32_e32 v48, v48, v49
	s_nop 1
	v_mov_b32_dpp v49, v48 row_ror:1 row_mask:0xf bank_mask:0xf
	v_pk_add_f32 v[24:25], v[24:25], v[44:45] op_sel_hi:[1,0] neg_lo:[0,1] neg_hi:[0,1]
	v_mov_b32_e32 v59, v31
	v_pk_add_f32 v[26:27], v[26:27], v[44:45] op_sel_hi:[1,0] neg_lo:[0,1] neg_hi:[0,1]
	v_pk_add_f32 v[20:21], v[20:21], v[44:45] op_sel_hi:[1,0] neg_lo:[0,1] neg_hi:[0,1]
	s_waitcnt lgkmcnt(0)
	v_add_f32_e32 v48, v48, v49
	v_mul_f32_e32 v52, 0x3a800000, v48
	v_pk_add_f32 v[48:49], v[12:13], v[52:53] op_sel_hi:[1,0] neg_lo:[0,1] neg_hi:[0,1]
	v_mov_b32_e32 v13, v42
	v_mov_b32_e32 v54, v49
	v_mov_b32_e32 v12, v48
	v_pk_mul_f32 v[54:55], v[54:55], v[54:55]
	v_pk_add_f32 v[14:15], v[14:15], v[52:53] op_sel_hi:[1,0] neg_lo:[0,1] neg_hi:[0,1]
	v_pk_fma_f32 v[54:55], v[12:13], v[12:13], v[54:55]
	v_mov_b32_e32 v56, v14
	v_pk_add_f32 v[8:9], v[8:9], v[52:53] op_sel_hi:[1,0] neg_lo:[0,1] neg_hi:[0,1]
	v_mov_b32_e32 v58, v15
	v_pk_fma_f32 v[54:55], v[56:57], v[56:57], v[54:55]
	v_mov_b32_e32 v56, v8
	v_pk_fma_f32 v[54:55], v[58:59], v[58:59], v[54:55]
	v_mov_b32_e32 v57, v24
	v_pk_add_f32 v[10:11], v[10:11], v[52:53] op_sel_hi:[1,0] neg_lo:[0,1] neg_hi:[0,1]
	v_mov_b32_e32 v58, v9
	v_mov_b32_e32 v59, v25
	v_pk_fma_f32 v[54:55], v[56:57], v[56:57], v[54:55]
	v_mov_b32_e32 v56, v10
	v_pk_fma_f32 v[54:55], v[58:59], v[58:59], v[54:55]
	v_mov_b32_e32 v57, v26
	v_pk_add_f32 v[4:5], v[4:5], v[52:53] op_sel_hi:[1,0] neg_lo:[0,1] neg_hi:[0,1]
	v_mov_b32_e32 v58, v11
	v_mov_b32_e32 v59, v27
	v_pk_fma_f32 v[54:55], v[56:57], v[56:57], v[54:55]
	v_mov_b32_e32 v56, v4
	v_pk_fma_f32 v[54:55], v[58:59], v[58:59], v[54:55]
	v_mov_b32_e32 v57, v20
	v_pk_add_f32 v[22:23], v[22:23], v[44:45] op_sel_hi:[1,0] neg_lo:[0,1] neg_hi:[0,1]
	v_pk_add_f32 v[6:7], v[6:7], v[52:53] op_sel_hi:[1,0] neg_lo:[0,1] neg_hi:[0,1]
	v_mov_b32_e32 v58, v5
	v_mov_b32_e32 v59, v21
	v_pk_fma_f32 v[54:55], v[56:57], v[56:57], v[54:55]
	v_pk_add_f32 v[16:17], v[16:17], v[44:45] op_sel_hi:[1,0] neg_lo:[0,1] neg_hi:[0,1]
	v_pk_add_f32 v[0:1], v[0:1], v[52:53] op_sel_hi:[1,0] neg_lo:[0,1] neg_hi:[0,1]
	v_pk_fma_f32 v[54:55], v[58:59], v[58:59], v[54:55]
	v_mov_b32_e32 v56, v6
	v_mov_b32_e32 v57, v22
	v_lshl_add_u64 v[28:29], v[46:47], 0, v[192:193]
	v_pk_mul_f32 v[46:47], v[16:17], v[16:17]
	v_lshl_add_u64 v[12:13], v[50:51], 0, v[192:193]
	v_pk_mul_f32 v[50:51], v[0:1], v[0:1]
	v_mov_b32_e32 v58, v7
	v_mov_b32_e32 v59, v23
	v_pk_fma_f32 v[54:55], v[56:57], v[56:57], v[54:55]
	v_pk_add_f32 v[18:19], v[18:19], v[44:45] op_sel_hi:[1,0] neg_lo:[0,1] neg_hi:[0,1]
	v_pk_fma_f32 v[54:55], v[58:59], v[58:59], v[54:55]
	v_mov_b32_e32 v56, v50
	v_mov_b32_e32 v57, v46
	v_pk_add_f32 v[2:3], v[2:3], v[52:53] op_sel_hi:[1,0] neg_lo:[0,1] neg_hi:[0,1]
	v_pk_mul_f32 v[44:45], v[18:19], v[18:19]
	v_pk_add_f32 v[54:55], v[56:57], v[54:55]
	v_pk_mul_f32 v[52:53], v[2:3], v[2:3]
	v_mov_b32_e32 v46, v51
	v_pk_add_f32 v[46:47], v[46:47], v[54:55]
	v_mov_b32_e32 v50, v52
	v_mov_b32_e32 v51, v44
	v_pk_add_f32 v[46:47], v[50:51], v[46:47]
	v_mov_b32_e32 v44, v53
	v_pk_add_f32 v[44:45], v[44:45], v[46:47]
	v_mov_b32_e32 v47, v45
	s_nop 1
	v_permlane32_swap_b32_e32 v47, v45
	v_mov_b32_e32 v46, v44
	s_nop 1
	v_permlane32_swap_b32_e32 v46, v44
	s_waitcnt lgkmcnt(0)
	v_pk_add_f32 v[44:45], v[44:45], v[46:47]
	v_mov_b32_e32 v47, v45
	s_nop 1
	v_permlane16_swap_b32_e32 v47, v45
	v_mov_b32_e32 v46, v44
	s_nop 1
	v_permlane16_swap_b32_e32 v46, v44
	s_waitcnt lgkmcnt(0)
	v_pk_add_f32 v[44:45], v[44:45], v[46:47]
	s_nop 1
	v_mov_b32_dpp v47, v45 row_ror:8 row_mask:0xf bank_mask:0xf
	s_nop 1
	v_mov_b32_dpp v46, v44 row_ror:8 row_mask:0xf bank_mask:0xf
	s_waitcnt lgkmcnt(0)
; template <int GRP>
; DI void ln_items(float* X, const float* gam, const float* bet, bf16_t* u2, const float* sc, const float* sh, int item0) {
;     ...
;     for (int j = 0; j < 4; ++j)
; #pragma unroll
;       for (int e = 0; e < 4; ++e) { const float d = v[g][j][e] - mu; q += d * d; }
; #pragma unroll
;     for (int off = 32; off >= 1; off >>= 1) q += __shfl_xor(q, off);
;     const float rstd = rsqrtf(q * (1.f / 1024.f) + 1e-5f);
; #pragma unroll
;     for (int j = 0; j < 4; ++j) {
;       const int col = j * 256 + lane * 4;
;       const f32x4 gg = *(const f32x4*)(gam + col), be = *(const f32x4*)(bet + col);
;       f32x4 y;
; #pragma unroll
;       for (int e = 0; e < 4; ++e) y[e] = (v[g][j][e] - mu) * rstd * gg[e] + be[e];
;       *(f32x4*)(X + tok * 1024 + col) = y;
	v_pk_add_f32 v[44:45], v[44:45], v[46:47]
	s_nop 1
	v_mov_b32_dpp v47, v45 row_ror:4 row_mask:0xf bank_mask:0xf
	s_nop 1
	v_mov_b32_dpp v46, v44 row_ror:4 row_mask:0xf bank_mask:0xf
	s_waitcnt lgkmcnt(0)
	v_pk_add_f32 v[44:45], v[44:45], v[46:47]
	s_nop 1
	v_mov_b32_dpp v47, v45 row_ror:2 row_mask:0xf bank_mask:0xf
	s_nop 1
	v_mov_b32_dpp v46, v44 row_ror:2 row_mask:0xf bank_mask:0xf
	s_waitcnt lgkmcnt(0)
	v_pk_add_f32 v[44:45], v[44:45], v[46:47]
	s_nop 1
	v_mov_b32_dpp v47, v45 row_ror:1 row_mask:0xf bank_mask:0xf
	s_nop 1
	v_mov_b32_dpp v46, v44 row_ror:1 row_mask:0xf bank_mask:0xf
	s_waitcnt lgkmcnt(0)
	v_pk_add_f32 v[44:45], v[44:45], v[46:47]
	s_nop 0
	v_pk_fma_f32 v[40:41], v[44:45], s[18:19], v[40:41] op_sel_hi:[1,0,0]
	s_nop 0
	v_mul_f32_e32 v44, 0x4b800000, v41
	v_cmp_gt_f32_e64 s[0:1], s39, v41
	v_cmp_gt_f32_e32 vcc, s39, v40
	s_nop 0
	v_cndmask_b32_e64 v41, v41, v44, s[0:1]
	v_rsq_f32_e32 v41, v41
	s_nop 0
	v_mul_f32_e32 v44, 0x45800000, v41
	v_cndmask_b32_e64 v44, v41, v44, s[0:1]
	v_pk_mul_f32 v[46:47], v[30:31], v[44:45] op_sel_hi:[1,0]
	v_pk_mul_f32 v[30:31], v[42:43], v[44:45] op_sel_hi:[1,0]
	v_pk_mul_f32 v[26:27], v[26:27], v[44:45] op_sel_hi:[1,0]
	s_waitcnt vmcnt(0)
	v_pk_fma_f32 v[30:31], v[32:33], v[30:31], v[36:37]
	v_pk_fma_f32 v[32:33], v[34:35], v[46:47], v[38:39]
	global_store_dwordx4 v[28:29], v[30:33], off
	global_load_dwordx4 v[30:33], v192, s[22:23] offset:1024
	s_nop 0
	global_load_dwordx4 v[34:37], v192, s[24:25] offset:1024
	v_pk_mul_f32 v[24:25], v[24:25], v[44:45] op_sel_hi:[1,0]
	v_pk_mul_f32 v[22:23], v[22:23], v[44:45] op_sel_hi:[1,0]
	v_pk_mul_f32 v[20:21], v[20:21], v[44:45] op_sel_hi:[1,0]
	v_pk_mul_f32 v[18:19], v[18:19], v[44:45] op_sel_hi:[1,0]
	v_pk_mul_f32 v[16:17], v[16:17], v[44:45] op_sel_hi:[1,0]
	s_waitcnt vmcnt(0)
	v_pk_fma_f32 v[24:25], v[30:31], v[24:25], v[34:35]
	v_pk_fma_f32 v[26:27], v[32:33], v[26:27], v[36:37]
	global_store_dwordx4 v[28:29], v[24:27], off offset:1024
	global_load_dwordx4 v[24:27], v192, s[22:23] offset:2048
	s_nop 0
	global_load_dwordx4 v[30:33], v192, s[24:25] offset:2048
	s_waitcnt vmcnt(0)
	v_pk_fma_f32 v[20:21], v[24:25], v[20:21], v[30:31]
	v_pk_fma_f32 v[22:23], v[26:27], v[22:23], v[32:33]
	global_store_dwordx4 v[28:29], v[20:23], off offset:2048
	global_load_dwordx4 v[20:23], v192, s[22:23] offset:3072
	s_nop 0
	global_load_dwordx4 v[24:27], v192, s[24:25] offset:3072
	s_waitcnt vmcnt(0)
	v_pk_fma_f32 v[16:17], v[20:21], v[16:17], v[24:25]
	v_pk_fma_f32 v[18:19], v[22:23], v[18:19], v[26:27]
	global_store_dwordx4 v[28:29], v[16:19], off offset:3072
	global_load_dwordx4 v[16:19], v192, s[22:23]
	s_nop 0
	global_load_dwordx4 v[20:23], v192, s[24:25]
	v_mul_f32_e32 v24, 0x4b800000, v40
	v_cndmask_b32_e32 v24, v40, v24, vcc
	v_rsq_f32_e32 v24, v24
	s_nop 0
	v_mul_f32_e32 v25, 0x45800000, v24
	v_cndmask_b32_e32 v24, v24, v25, vcc
	v_pk_mul_f32 v[26:27], v[14:15], v[24:25] op_sel_hi:[1,0]
	v_pk_mul_f32 v[14:15], v[48:49], v[24:25] op_sel_hi:[1,0]
	v_pk_mul_f32 v[10:11], v[10:11], v[24:25] op_sel_hi:[1,0]
	v_pk_mul_f32 v[8:9], v[8:9], v[24:25] op_sel_hi:[1,0]
	v_pk_mul_f32 v[6:7], v[6:7], v[24:25] op_sel_hi:[1,0]
	v_pk_mul_f32 v[4:5], v[4:5], v[24:25] op_sel_hi:[1,0]
	v_pk_mul_f32 v[2:3], v[2:3], v[24:25] op_sel_hi:[1,0]
	v_pk_mul_f32 v[0:1], v[0:1], v[24:25] op_sel_hi:[1,0]
	s_waitcnt vmcnt(0)
	v_pk_fma_f32 v[14:15], v[16:17], v[14:15], v[20:21]
	v_pk_fma_f32 v[16:17], v[18:19], v[26:27], v[22:23]
	global_store_dwordx4 v[12:13], v[14:17], off
	global_load_dwordx4 v[14:17], v192, s[22:23] offset:1024
	s_nop 0
	global_load_dwordx4 v[18:21], v192, s[24:25] offset:1024
	s_waitcnt vmcnt(0)
	v_pk_fma_f32 v[8:9], v[14:15], v[8:9], v[18:19]
	v_pk_fma_f32 v[10:11], v[16:17], v[10:11], v[20:21]
	global_store_dwordx4 v[12:13], v[8:11], off offset:1024
	global_load_dwordx4 v[8:11], v192, s[22:23] offset:2048
	s_nop 0
	global_load_dwordx4 v[14:17], v192, s[24:25] offset:2048
	s_waitcnt vmcnt(0)
	v_pk_fma_f32 v[4:5], v[8:9], v[4:5], v[14:15]
	v_pk_fma_f32 v[6:7], v[10:11], v[6:7], v[16:17]
	global_store_dwordx4 v[12:13], v[4:7], off offset:2048
	global_load_dwordx4 v[4:7], v192, s[22:23] offset:3072
	s_nop 0
	global_load_dwordx4 v[8:11], v192, s[24:25] offset:3072
	s_waitcnt vmcnt(0)
	v_pk_fma_f32 v[0:1], v[4:5], v[0:1], v[8:9]
	v_pk_fma_f32 v[2:3], v[6:7], v[2:3], v[10:11]
	global_store_dwordx4 v[12:13], v[0:3], off offset:3072
	s_cbranch_scc0 .LBB0_156
	v_readlane_b32 s0, v249, 5
	s_add_i32 s17, s17, s0
	v_readlane_b32 s0, v250, 44
	s_add_i32 s8, s8, s0
	v_readlane_b32 s0, v250, 60
	s_add_i32 s16, s16, s0
	s_cmpk_gt_i32 s17, 0x1ff
	s_barrier
	v_readlane_b32 s1, v249, 6
	s_cbranch_scc0 .LBB0_131

; DI int TIDX() { int t = __builtin_amdgcn_workitem_id_x(); asm volatile("" : "+v"(t)); return t; }
; template <int GRP>
; DI void ln_items(float* X, const float* gam, const float* bet, bf16_t* u2, const float* sc, const float* sh, int item0) {
;   const int tid = TIDX(), lane = tid & 63, wave = tid >> 6;
;   f32x4 v[GRP][4];
; #pragma unroll
;   for (int g = 0; g < GRP; ++g) {
;     const size_t tok = (size_t)(item0 + g) * 4 + wave;
; #pragma unroll
;     for (int j = 0; j < 4; ++j) v[g][j] = *(const f32x4*)(X + tok * 1024 + j * 256 + lane * 4);
;   }
; #pragma unroll
;   for (int g = 0; g < GRP; ++g) {
;     const size_t tok = (size_t)(item0 + g) * 4 + wave;
;     const int b = (int)(tok >> 13);
;     float s = 0.f;
; #pragma unroll
;     for (int j = 0; j < 4; ++j) s += v[g][j][0] + v[g][j][1] + v[g][j][2] + v[g][j][3];
; #pragma unroll
;     for (int off = 32; off >= 1; off >>= 1) s += __shfl_xor(s, off);
;     const float mu = s * (1.f / 1024.f);
.LBB0_222:
	v_mov_b32_e32 v2, v218
	s_add_i32 s8, s14, s5
	v_ashrrev_i32_e32 v64, 6, v2
	v_ashrrev_i32_e32 v65, 31, v64
	v_lshlrev_b32_e32 v2, 2, v2
	s_add_i32 s0, s8, 4
	v_lshlrev_b64 v[0:1], 12, v[64:65]
	v_and_b32_e32 v95, 0xfc, v2
	v_lshl_add_u64 v[0:1], s[92:93], 0, v[0:1]
	v_lshlrev_b32_e32 v192, 2, v95
	s_ashr_i32 s1, s0, 31
	v_lshl_add_u64 v[0:1], v[0:1], 0, v[192:193]
	s_lshl_b64 s[6:7], s[0:1], 14
	v_lshl_add_u64 v[2:3], v[0:1], 0, s[6:7]
	global_load_dwordx4 v[48:51], v[2:3], off
	global_load_dwordx4 v[60:63], v[2:3], off offset:1024
	global_load_dwordx4 v[56:59], v[2:3], off offset:2048
	global_load_dwordx4 v[52:55], v[2:3], off offset:3072
	v_mbcnt_hi_u32_b32 v70, -1, v222
	v_and_b32_e32 v66, 64, v70
	v_add_u32_e32 v71, 64, v66
	s_add_i32 s12, s8, 5
	s_ashr_i32 s13, s12, 31
	s_add_i32 s10, s8, 6
	s_lshl_b64 s[6:7], s[12:13], 14
	s_ashr_i32 s11, s10, 31
	s_add_i32 s8, s8, 7
	v_lshl_add_u64 v[2:3], v[0:1], 0, s[6:7]
	s_lshl_b64 s[6:7], s[10:11], 14
	s_ashr_i32 s9, s8, 31
	global_load_dwordx4 v[32:35], v[2:3], off
	global_load_dwordx4 v[44:47], v[2:3], off offset:1024
	global_load_dwordx4 v[40:43], v[2:3], off offset:2048
	global_load_dwordx4 v[36:39], v[2:3], off offset:3072
	v_lshl_add_u64 v[2:3], v[0:1], 0, s[6:7]
	s_lshl_b64 s[6:7], s[8:9], 14
	v_lshl_add_u64 v[78:79], s[0:1], 2, v[64:65]
	v_readlane_b32 s0, v251, 60
	v_lshl_add_u64 v[4:5], v[0:1], 0, s[6:7]
	v_readlane_b32 s1, v251, 61
	global_load_dwordx4 v[16:19], v[2:3], off
	global_load_dwordx4 v[28:31], v[2:3], off offset:1024
	global_load_dwordx4 v[24:27], v[2:3], off offset:2048
	global_load_dwordx4 v[20:23], v[2:3], off offset:3072
	s_nop 0
	global_load_dwordx4 v[0:3], v[4:5], off
	global_load_dwordx4 v[12:15], v[4:5], off offset:1024
	global_load_dwordx4 v[8:11], v[4:5], off offset:2048
	s_nop 0
	global_load_dwordx4 v[4:7], v[4:5], off offset:3072
	v_readlane_b32 s16, v249, 43
	global_load_dwordx4 v[96:99], v192, s[0:1]
	v_readlane_b32 s0, v251, 56
	v_readlane_b32 s1, v251, 57
	v_readlane_b32 s17, v249, 44
	v_readlane_b32 s6, v250, 0
	v_readlane_b32 s7, v250, 1
	s_waitcnt vmcnt(16)
	v_mov_b32_e32 v66, v48
	s_waitcnt vmcnt(15)
	v_mov_b32_e32 v67, v60
	v_mov_b32_e32 v68, v49
	v_mov_b32_e32 v69, v61
	v_pk_add_f32 v[66:67], v[66:67], v[68:69]
	v_mov_b32_e32 v68, v50
	v_mov_b32_e32 v69, v62
	v_pk_add_f32 v[66:67], v[68:69], v[66:67]
	v_mov_b32_e32 v68, v51
	v_mov_b32_e32 v69, v63
	v_pk_add_f32 v[66:67], v[68:69], v[66:67]
	s_waitcnt vmcnt(14)
	v_mov_b32_e32 v68, v57
	v_add_f32_e32 v66, 0, v66
	v_add_f32_e32 v72, v66, v67
	v_mov_b32_e32 v66, v56
	s_waitcnt vmcnt(13)
	v_mov_b32_e32 v67, v52
	v_mov_b32_e32 v69, v53
	v_pk_add_f32 v[66:67], v[66:67], v[68:69]
	v_mov_b32_e32 v68, v58
	v_mov_b32_e32 v69, v54
	v_pk_add_f32 v[66:67], v[68:69], v[66:67]
	v_mov_b32_e32 v68, v59
	v_mov_b32_e32 v69, v55
	v_pk_add_f32 v[66:67], v[68:69], v[66:67]
	global_load_dwordx4 v[100:103], v192, s[0:1]
	v_add_f32_e32 v66, v72, v66
	v_add_f32_e32 v66, v66, v67
	v_xor_b32_e32 v67, 32, v70
	v_cmp_lt_i32_e32 vcc, v67, v71
	s_nop 1
	v_cndmask_b32_e32 v67, v70, v67, vcc
	v_lshlrev_b32_e32 v89, 2, v67
	v_mov_b32_e32 v67, v66
	s_nop 1
	v_permlane32_swap_b32_e32 v67, v66
	s_waitcnt lgkmcnt(0)
	v_add_f32_e32 v66, v66, v67
	v_xor_b32_e32 v67, 16, v70
	v_cmp_lt_i32_e32 vcc, v67, v71
	s_nop 1
	v_cndmask_b32_e32 v67, v70, v67, vcc
	v_lshlrev_b32_e32 v90, 2, v67
	v_mov_b32_e32 v67, v66
	s_nop 1
	v_permlane16_swap_b32_e32 v67, v66
	s_waitcnt lgkmcnt(0)
	v_add_f32_e32 v66, v66, v67
	v_xor_b32_e32 v67, 8, v70
	v_cmp_lt_i32_e32 vcc, v67, v71
	s_nop 1
	v_cndmask_b32_e32 v67, v70, v67, vcc
	v_lshlrev_b32_e32 v91, 2, v67
	s_nop 1
	v_mov_b32_dpp v67, v66 row_ror:8 row_mask:0xf bank_mask:0xf
	s_waitcnt lgkmcnt(0)
	v_add_f32_e32 v66, v66, v67
	v_xor_b32_e32 v67, 4, v70
	v_cmp_lt_i32_e32 vcc, v67, v71
	s_nop 1
	v_cndmask_b32_e32 v67, v70, v67, vcc
	v_lshlrev_b32_e32 v92, 2, v67
	s_nop 1
	v_mov_b32_dpp v67, v66 row_ror:4 row_mask:0xf bank_mask:0xf
	s_waitcnt lgkmcnt(0)
	v_add_f32_e32 v66, v66, v67
	v_xor_b32_e32 v67, 2, v70
	v_cmp_lt_i32_e32 vcc, v67, v71
	s_nop 1
	v_cndmask_b32_e32 v67, v70, v67, vcc
	v_lshlrev_b32_e32 v93, 2, v67
	s_nop 1
	v_mov_b32_dpp v67, v66 row_ror:2 row_mask:0xf bank_mask:0xf
	s_waitcnt lgkmcnt(0)
; DI unsigned pack2(float a, float b) { const hwf32x2 f = {a, b}; return __builtin_bit_cast(unsigned, __builtin_convertvector(f, hwbf16x2)); }
; template <int GRP>
; DI void ln_items(float* X, const float* gam, const float* bet, bf16_t* u2, const float* sc, const float* sh, int item0) {
;     ...
; #pragma unroll
;     for (int j = 0; j < 4; ++j) s += v[g][j][0] + v[g][j][1] + v[g][j][2] + v[g][j][3];
; #pragma unroll
;     for (int off = 32; off >= 1; off >>= 1) s += __shfl_xor(s, off);
;     const float mu = s * (1.f / 1024.f);
;     float q = 0.f;
; #pragma unroll
;     for (int j = 0; j < 4; ++j)
; #pragma unroll
;       for (int e = 0; e < 4; ++e) { const float d = v[g][j][e] - mu; q += d * d; }
; #pragma unroll
;     for (int off = 32; off >= 1; off >>= 1) q += __shfl_xor(q, off);
;     const float rstd = rsqrtf(q * (1.f / 1024.f) + 1e-5f);
; #pragma unroll
;     for (int j = 0; j < 4; ++j) {
;       const int col = j * 256 + lane * 4;
;       const f32x4 gg = *(const f32x4*)(gam + col), be = *(const f32x4*)(bet + col);
;       f32x4 y;
; #pragma unroll
;       for (int e = 0; e < 4; ++e) y[e] = (v[g][j][e] - mu) * rstd * gg[e] + be[e];
;       *(f32x4*)(X + tok * 1024 + col) = y;
;       if (u2) {
;         const f32x4 s4 = *(const f32x4*)(sc + b * 6144 + col), h4 = *(const f32x4*)(sh + b * 6144 + col);
;         uint2 o;
;         o.x = pack2(y[0] * (1.f + s4[0]) + h4[0], y[1] * (1.f + s4[1]) + h4[1]);
;         o.y = pack2(y[2] * (1.f + s4[2]) + h4[2], y[3] * (1.f + s4[3]) + h4[3]);
;         *(uint2*)(u2 + tok * 1024 + col) = o;
;       }
;     }
	v_add_f32_e32 v66, v66, v67
	v_xor_b32_e32 v67, 1, v70
	v_cmp_lt_i32_e32 vcc, v67, v71
	s_nop 1
	v_cndmask_b32_e32 v67, v70, v67, vcc
	v_lshlrev_b32_e32 v94, 2, v67
	s_nop 1
	v_mov_b32_dpp v67, v66 row_ror:1 row_mask:0xf bank_mask:0xf
	s_waitcnt lgkmcnt(0)
	v_add_f32_e32 v66, v66, v67
	v_mul_f32_e32 v88, 0x3a800000, v66
	v_pk_add_f32 v[72:73], v[58:59], v[88:89] op_sel_hi:[1,0] neg_lo:[0,1] neg_hi:[0,1]
	v_alignbit_b32 v58, v79, v78, 13
	v_mul_lo_u32 v59, v58, s58
	v_mov_b32_e32 v58, v193
	v_pk_add_f32 v[48:49], v[48:49], v[88:89] op_sel_hi:[1,0] neg_lo:[0,1] neg_hi:[0,1]
	v_ashrrev_i64 v[58:59], 30, v[58:59]
	v_pk_add_f32 v[50:51], v[50:51], v[88:89] op_sel_hi:[1,0] neg_lo:[0,1] neg_hi:[0,1]
	v_pk_mul_f32 v[104:105], v[48:49], v[48:49]
	v_pk_add_f32 v[74:75], v[60:61], v[88:89] op_sel_hi:[1,0] neg_lo:[0,1] neg_hi:[0,1]
	v_pk_add_f32 v[76:77], v[62:63], v[88:89] op_sel_hi:[1,0] neg_lo:[0,1] neg_hi:[0,1]
	v_pk_add_f32 v[70:71], v[56:57], v[88:89] op_sel_hi:[1,0] neg_lo:[0,1] neg_hi:[0,1]
	v_pk_add_f32 v[66:67], v[52:53], v[88:89] op_sel_hi:[1,0] neg_lo:[0,1] neg_hi:[0,1]
	v_pk_add_f32 v[68:69], v[54:55], v[88:89] op_sel_hi:[1,0] neg_lo:[0,1] neg_hi:[0,1]
	v_lshlrev_b64 v[52:53], 12, v[78:79]
	v_lshl_add_u64 v[62:63], s[16:17], 0, v[58:59]
	v_lshl_add_u64 v[60:61], s[66:67], 0, v[58:59]
	v_lshlrev_b64 v[58:59], 11, v[78:79]
	v_pk_mul_f32 v[78:79], v[50:51], v[50:51]
	v_add_f32_e32 v88, v104, v105
	v_add_f32_e32 v78, v78, v88
	v_pk_mul_f32 v[80:81], v[74:75], v[74:75]
	v_add_f32_e32 v78, v79, v78
	v_add_f32_e32 v78, v80, v78
	v_pk_mul_f32 v[82:83], v[76:77], v[76:77]
	v_add_f32_e32 v78, v81, v78
	v_add_f32_e32 v78, v82, v78
	v_pk_mul_f32 v[56:57], v[70:71], v[70:71]
	v_add_f32_e32 v78, v83, v78
	v_add_f32_e32 v56, v56, v78
	v_pk_mul_f32 v[84:85], v[72:73], v[72:73]
	v_add_f32_e32 v56, v57, v56
	v_add_f32_e32 v56, v84, v56
	v_pk_mul_f32 v[86:87], v[66:67], v[66:67]
	v_add_f32_e32 v56, v85, v56
	v_add_f32_e32 v56, v86, v56
	v_pk_mul_f32 v[54:55], v[68:69], v[68:69]
	v_add_f32_e32 v56, v87, v56
	v_add_f32_e32 v54, v54, v56
	v_add_f32_e32 v54, v55, v54
	v_mov_b32_e32 v55, v54
	s_nop 1
	v_permlane32_swap_b32_e32 v55, v54
	v_lshl_add_u64 v[52:53], s[92:93], 0, v[52:53]
	v_lshl_add_u64 v[78:79], v[52:53], 0, v[192:193]
	v_cndmask_b32_e64 v52, 0, 1, s[6:7]
	v_lshl_add_u64 v[58:59], s[96:97], 0, v[58:59]
	s_waitcnt lgkmcnt(0)
	v_add_f32_e32 v54, v54, v55
	v_mov_b32_e32 v55, v54
	s_nop 1
	v_permlane16_swap_b32_e32 v55, v54
	v_cmp_ne_u32_e64 s[0:1], 1, v52
	v_lshlrev_b32_e32 v52, 1, v95
	s_waitcnt lgkmcnt(0)
	v_add_f32_e32 v54, v54, v55
	s_nop 1
	v_mov_b32_dpp v55, v54 row_ror:8 row_mask:0xf bank_mask:0xf
	s_waitcnt lgkmcnt(0)
	v_add_f32_e32 v54, v54, v55
	s_nop 1
	v_mov_b32_dpp v55, v54 row_ror:4 row_mask:0xf bank_mask:0xf
	s_waitcnt lgkmcnt(0)
	v_add_f32_e32 v54, v54, v55
	s_nop 1
	v_mov_b32_dpp v55, v54 row_ror:2 row_mask:0xf bank_mask:0xf
	s_waitcnt lgkmcnt(0)
	v_add_f32_e32 v54, v54, v55
	s_nop 1
	v_mov_b32_dpp v55, v54 row_ror:1 row_mask:0xf bank_mask:0xf
	s_waitcnt lgkmcnt(0)
	v_add_f32_e32 v54, v54, v55
	v_fmamk_f32 v54, v54, 0x3a800000, v220
	v_cmp_gt_f32_e32 vcc, s39, v54
	v_mul_f32_e32 v55, 0x4b800000, v54
	s_nop 0
	v_cndmask_b32_e32 v54, v54, v55, vcc
	v_rsq_f32_e32 v54, v54
	s_nop 0
	v_mul_f32_e32 v55, 0x45800000, v54
	v_cndmask_b32_e32 v80, v54, v55, vcc
	v_pk_mul_f32 v[48:49], v[48:49], v[80:81] op_sel_hi:[1,0]
	v_pk_mul_f32 v[50:51], v[50:51], v[80:81] op_sel_hi:[1,0]
	s_waitcnt vmcnt(0)
	v_pk_fma_f32 v[48:49], v[96:97], v[48:49], v[100:101]
	v_pk_fma_f32 v[50:51], v[98:99], v[50:51], v[102:103]
	s_andn2_b64 vcc, exec, s[6:7]
	global_store_dwordx4 v[78:79], v[48:51], off
	s_cbranch_vccnz .LBB0_224
	v_lshl_add_u64 v[54:55], v[62:63], 0, v[192:193]
	global_load_dwordx4 v[54:57], v[54:55], off
	v_lshl_add_u64 v[82:83], v[60:61], 0, v[192:193]
	global_load_dwordx4 v[82:85], v[82:83], off
	v_mov_b32_e32 v53, v193
	s_waitcnt vmcnt(1)
	v_pk_add_f32 v[54:55], v[54:55], 1.0 op_sel_hi:[1,0]
	s_waitcnt vmcnt(0)
	v_pk_fma_f32 v[48:49], v[48:49], v[54:55], v[82:83]
	v_pk_add_f32 v[54:55], v[56:57], 1.0 op_sel_hi:[1,0]
	v_cvt_pk_bf16_f32 v48, v48, v49
	v_pk_fma_f32 v[50:51], v[50:51], v[54:55], v[84:85]
	s_nop 0
	v_cvt_pk_bf16_f32 v49, v50, v51
	v_lshl_add_u64 v[50:51], v[58:59], 0, v[52:53]
	global_store_dwordx2 v[50:51], v[48:49], off

; DI unsigned pack2(float a, float b) { const hwf32x2 f = {a, b}; return __builtin_bit_cast(unsigned, __builtin_convertvector(f, hwbf16x2)); }
; template <int GRP>
; DI void ln_items(float* X, const float* gam, const float* bet, bf16_t* u2, const float* sc, const float* sh, int item0) {
;     ...
;   for (int g = 0; g < GRP; ++g) {
;     const size_t tok = (size_t)(item0 + g) * 4 + wave;
;     const int b = (int)(tok >> 13);
;     float s = 0.f;
; #pragma unroll
;     for (int j = 0; j < 4; ++j) s += v[g][j][0] + v[g][j][1] + v[g][j][2] + v[g][j][3];
; #pragma unroll
;     for (int off = 32; off >= 1; off >>= 1) s += __shfl_xor(s, off);
;     const float mu = s * (1.f / 1024.f);
;     float q = 0.f;
; #pragma unroll
;     for (int j = 0; j < 4; ++j)
; #pragma unroll
;       for (int e = 0; e < 4; ++e) { const float d = v[g][j][e] - mu; q += d * d; }
; #pragma unroll
;     for (int off = 32; off >= 1; off >>= 1) q += __shfl_xor(q, off);
;     const float rstd = rsqrtf(q * (1.f / 1024.f) + 1e-5f);
; #pragma unroll
;     for (int j = 0; j < 4; ++j) {
;       const int col = j * 256 + lane * 4;
;       const f32x4 gg = *(const f32x4*)(gam + col), be = *(const f32x4*)(bet + col);
;       f32x4 y;
; #pragma unroll
;       for (int e = 0; e < 4; ++e) y[e] = (v[g][j][e] - mu) * rstd * gg[e] + be[e];
;       *(f32x4*)(X + tok * 1024 + col) = y;
;       if (u2) {
;         const f32x4 s4 = *(const f32x4*)(sc + b * 6144 + col), h4 = *(const f32x4*)(sh + b * 6144 + col);
;         uint2 o;
;         o.x = pack2(y[0] * (1.f + s4[0]) + h4[0], y[1] * (1.f + s4[1]) + h4[1]);
;         o.y = pack2(y[2] * (1.f + s4[2]) + h4[2], y[3] * (1.f + s4[3]) + h4[3]);
;         *(uint2*)(u2 + tok * 1024 + col) = o;
;       }
;     }
.LBB0_230:
	s_nop 0
	v_mov_b32_e32 v48, v32
	v_mov_b32_e32 v49, v44
	v_mov_b32_e32 v50, v33
	v_mov_b32_e32 v51, v45
	v_pk_add_f32 v[48:49], v[48:49], v[50:51]
	v_mov_b32_e32 v50, v34
	v_mov_b32_e32 v51, v46
	v_pk_add_f32 v[48:49], v[50:51], v[48:49]
	v_mov_b32_e32 v50, v35
	v_mov_b32_e32 v51, v47
	v_pk_add_f32 v[48:49], v[50:51], v[48:49]
	v_mov_b32_e32 v50, v41
	v_add_f32_e32 v48, 0, v48
	v_add_f32_e32 v53, v48, v49
	v_mov_b32_e32 v48, v40
	v_mov_b32_e32 v49, v36
	v_mov_b32_e32 v51, v37
	v_pk_add_f32 v[48:49], v[48:49], v[50:51]
	v_mov_b32_e32 v50, v42
	v_mov_b32_e32 v51, v38
	v_pk_add_f32 v[48:49], v[50:51], v[48:49]
	v_mov_b32_e32 v50, v43
	v_mov_b32_e32 v51, v39
	v_pk_add_f32 v[48:49], v[50:51], v[48:49]
	global_load_dwordx4 v[66:69], v[54:55], off
	global_load_dwordx4 v[70:73], v[56:57], off
	v_add_f32_e32 v48, v53, v48
	v_add_f32_e32 v48, v48, v49
	v_mov_b32_e32 v49, v48
	s_nop 1
	v_permlane32_swap_b32_e32 v49, v48
	s_waitcnt lgkmcnt(0)
	v_add_f32_e32 v48, v48, v49
	v_mov_b32_e32 v49, v48
	s_nop 1
	v_permlane16_swap_b32_e32 v49, v48
	s_waitcnt lgkmcnt(0)
	v_add_f32_e32 v48, v48, v49
	s_nop 1
	v_mov_b32_dpp v49, v48 row_ror:8 row_mask:0xf bank_mask:0xf
	s_waitcnt lgkmcnt(0)
	v_add_f32_e32 v48, v48, v49
	s_nop 1
	v_mov_b32_dpp v49, v48 row_ror:4 row_mask:0xf bank_mask:0xf
	s_waitcnt lgkmcnt(0)
	v_add_f32_e32 v48, v48, v49
	s_nop 1
	v_mov_b32_dpp v49, v48 row_ror:2 row_mask:0xf bank_mask:0xf
	s_waitcnt lgkmcnt(0)
	v_add_f32_e32 v48, v48, v49
	s_nop 1
	v_mov_b32_dpp v49, v48 row_ror:1 row_mask:0xf bank_mask:0xf
	s_waitcnt lgkmcnt(0)
	v_add_f32_e32 v48, v48, v49
	v_mul_f32_e32 v48, 0x3a800000, v48
	v_pk_add_f32 v[32:33], v[32:33], v[48:49] op_sel_hi:[1,0] neg_lo:[0,1] neg_hi:[0,1]
	v_pk_add_f32 v[62:63], v[44:45], v[48:49] op_sel_hi:[1,0] neg_lo:[0,1] neg_hi:[0,1]
	v_pk_add_f32 v[60:61], v[46:47], v[48:49] op_sel_hi:[1,0] neg_lo:[0,1] neg_hi:[0,1]
	v_pk_add_f32 v[50:51], v[40:41], v[48:49] op_sel_hi:[1,0] neg_lo:[0,1] neg_hi:[0,1]
	v_pk_add_f32 v[58:59], v[42:43], v[48:49] op_sel_hi:[1,0] neg_lo:[0,1] neg_hi:[0,1]
	v_pk_add_f32 v[40:41], v[36:37], v[48:49] op_sel_hi:[1,0] neg_lo:[0,1] neg_hi:[0,1]
	v_pk_add_f32 v[38:39], v[38:39], v[48:49] op_sel_hi:[1,0] neg_lo:[0,1] neg_hi:[0,1]
	v_pk_add_f32 v[34:35], v[34:35], v[48:49] op_sel_hi:[1,0] neg_lo:[0,1] neg_hi:[0,1]
	v_pk_mul_f32 v[48:49], v[32:33], v[32:33]
	v_pk_mul_f32 v[78:79], v[34:35], v[34:35]
	v_add_f32_e32 v48, v48, v49
	v_add_f32_e32 v48, v78, v48
	v_pk_mul_f32 v[44:45], v[62:63], v[62:63]
	v_add_f32_e32 v48, v79, v48
	v_add_f32_e32 v44, v44, v48
	v_pk_mul_f32 v[46:47], v[60:61], v[60:61]
	v_add_f32_e32 v44, v45, v44
	v_add_f32_e32 v44, v46, v44
	v_pk_mul_f32 v[74:75], v[50:51], v[50:51]
	v_add_f32_e32 v44, v47, v44
	v_add_f32_e32 v44, v74, v44
	v_pk_mul_f32 v[42:43], v[58:59], v[58:59]
	v_add_f32_e32 v44, v75, v44
	v_add_f32_e32 v42, v42, v44
	v_pk_mul_f32 v[36:37], v[40:41], v[40:41]
	v_add_f32_e32 v42, v43, v42
	v_add_f32_e32 v36, v36, v42
	v_pk_mul_f32 v[76:77], v[38:39], v[38:39]
	v_add_f32_e32 v36, v37, v36
	v_add_f32_e32 v36, v76, v36
	v_add_f32_e32 v36, v77, v36
	v_mov_b32_e32 v37, v36
	s_nop 1
	v_permlane32_swap_b32_e32 v37, v36
	s_waitcnt lgkmcnt(0)
	v_add_f32_e32 v36, v36, v37
	v_mov_b32_e32 v37, v36
	s_nop 1
	v_permlane16_swap_b32_e32 v37, v36
	s_waitcnt lgkmcnt(0)
	v_add_f32_e32 v36, v36, v37
	s_nop 1
	v_mov_b32_dpp v37, v36 row_ror:8 row_mask:0xf bank_mask:0xf
	s_waitcnt lgkmcnt(0)
	v_add_f32_e32 v42, v36, v37
	s_nop 1
	v_mov_b32_dpp v43, v42 row_ror:4 row_mask:0xf bank_mask:0xf
	v_lshl_add_u64 v[36:37], s[12:13], 2, v[64:65]
	v_alignbit_b32 v47, v37, v36, 13
	v_lshlrev_b64 v[44:45], 12, v[36:37]
	v_lshlrev_b64 v[36:37], 11, v[36:37]
	s_waitcnt lgkmcnt(0)
	v_add_f32_e32 v43, v42, v43
	s_nop 1
	v_mov_b32_dpp v46, v43 row_ror:2 row_mask:0xf bank_mask:0xf
	v_mov_b32_e32 v42, v193
	v_lshl_add_u64 v[44:45], s[92:93], 0, v[44:45]
	v_lshl_add_u64 v[36:37], s[96:97], 0, v[36:37]
	s_waitcnt lgkmcnt(0)
	v_add_f32_e32 v46, v43, v46
	s_nop 1
	v_mov_b32_dpp v48, v46 row_ror:1 row_mask:0xf bank_mask:0xf
	v_mul_lo_u32 v43, v47, s6
	v_ashrrev_i64 v[42:43], 30, v[42:43]
	s_waitcnt lgkmcnt(0)
	v_add_f32_e32 v46, v46, v48
	v_fmamk_f32 v46, v46, 0x3a800000, v220
	v_mul_f32_e32 v47, 0x4b800000, v46
	v_cmp_gt_f32_e32 vcc, s39, v46
	s_nop 1
	v_cndmask_b32_e32 v46, v46, v47, vcc
	v_rsq_f32_e32 v48, v46
	v_lshl_add_u64 v[46:47], v[44:45], 0, v[192:193]
	v_lshl_add_u64 v[44:45], s[16:17], 0, v[42:43]
	v_lshl_add_u64 v[42:43], s[66:67], 0, v[42:43]
	v_mul_f32_e32 v49, 0x45800000, v48
	v_cndmask_b32_e32 v48, v48, v49, vcc
	v_pk_mul_f32 v[32:33], v[32:33], v[48:49] op_sel_hi:[1,0]
	v_pk_mul_f32 v[34:35], v[34:35], v[48:49] op_sel_hi:[1,0]
	s_waitcnt vmcnt(0)
	v_pk_fma_f32 v[32:33], v[66:67], v[32:33], v[70:71]
	v_pk_fma_f32 v[34:35], v[68:69], v[34:35], v[72:73]
	s_and_b64 vcc, exec, s[0:1]
	global_store_dwordx4 v[46:47], v[32:35], off
	s_cbranch_vccnz .LBB0_232
	v_lshl_add_u64 v[66:67], v[44:45], 0, v[192:193]
	global_load_dwordx4 v[66:69], v[66:67], off
	v_lshl_add_u64 v[70:71], v[42:43], 0, v[192:193]
	global_load_dwordx4 v[70:73], v[70:71], off
	v_mov_b32_e32 v53, v193
	s_waitcnt vmcnt(1)
	v_pk_add_f32 v[66:67], v[66:67], 1.0 op_sel_hi:[1,0]
	s_waitcnt vmcnt(0)
	v_pk_fma_f32 v[32:33], v[32:33], v[66:67], v[70:71]
	v_pk_add_f32 v[66:67], v[68:69], 1.0 op_sel_hi:[1,0]
	v_cvt_pk_bf16_f32 v32, v32, v33
	v_pk_fma_f32 v[34:35], v[34:35], v[66:67], v[72:73]
	s_nop 0
	v_cvt_pk_bf16_f32 v33, v34, v35
	v_lshl_add_u64 v[34:35], v[36:37], 0, v[52:53]
	global_store_dwordx2 v[34:35], v[32:33], off

; DI unsigned pack2(float a, float b) { const hwf32x2 f = {a, b}; return __builtin_bit_cast(unsigned, __builtin_convertvector(f, hwbf16x2)); }
; template <int GRP>
; DI void ln_items(float* X, const float* gam, const float* bet, bf16_t* u2, const float* sc, const float* sh, int item0) {
;     ...
;   for (int g = 0; g < GRP; ++g) {
;     const size_t tok = (size_t)(item0 + g) * 4 + wave;
;     const int b = (int)(tok >> 13);
;     float s = 0.f;
; #pragma unroll
;     for (int j = 0; j < 4; ++j) s += v[g][j][0] + v[g][j][1] + v[g][j][2] + v[g][j][3];
; #pragma unroll
;     for (int off = 32; off >= 1; off >>= 1) s += __shfl_xor(s, off);
;     const float mu = s * (1.f / 1024.f);
;     float q = 0.f;
; #pragma unroll
;     for (int j = 0; j < 4; ++j)
; #pragma unroll
;       for (int e = 0; e < 4; ++e) { const float d = v[g][j][e] - mu; q += d * d; }
; #pragma unroll
;     for (int off = 32; off >= 1; off >>= 1) q += __shfl_xor(q, off);
;     const float rstd = rsqrtf(q * (1.f / 1024.f) + 1e-5f);
; #pragma unroll
;     for (int j = 0; j < 4; ++j) {
;       const int col = j * 256 + lane * 4;
;       const f32x4 gg = *(const f32x4*)(gam + col), be = *(const f32x4*)(bet + col);
;       f32x4 y;
; #pragma unroll
;       for (int e = 0; e < 4; ++e) y[e] = (v[g][j][e] - mu) * rstd * gg[e] + be[e];
;       *(f32x4*)(X + tok * 1024 + col) = y;
;       if (u2) {
;         const f32x4 s4 = *(const f32x4*)(sc + b * 6144 + col), h4 = *(const f32x4*)(sh + b * 6144 + col);
;         uint2 o;
;         o.x = pack2(y[0] * (1.f + s4[0]) + h4[0], y[1] * (1.f + s4[1]) + h4[1]);
;         o.y = pack2(y[2] * (1.f + s4[2]) + h4[2], y[3] * (1.f + s4[3]) + h4[3]);
;         *(uint2*)(u2 + tok * 1024 + col) = o;
;       }
;     }
.LBB0_238:
	s_nop 0
	v_mov_b32_e32 v32, v16
	v_mov_b32_e32 v33, v28
	v_mov_b32_e32 v34, v17
	v_mov_b32_e32 v35, v29
	v_pk_add_f32 v[32:33], v[32:33], v[34:35]
	v_mov_b32_e32 v34, v18
	v_mov_b32_e32 v35, v30
	v_pk_add_f32 v[32:33], v[34:35], v[32:33]
	v_mov_b32_e32 v34, v19
	v_mov_b32_e32 v35, v31
	v_pk_add_f32 v[32:33], v[34:35], v[32:33]
	v_mov_b32_e32 v34, v25
	v_add_f32_e32 v32, 0, v32
	v_add_f32_e32 v36, v32, v33
	v_mov_b32_e32 v32, v24
	v_mov_b32_e32 v33, v20
	v_mov_b32_e32 v35, v21
	v_pk_add_f32 v[32:33], v[32:33], v[34:35]
	v_mov_b32_e32 v34, v26
	v_mov_b32_e32 v35, v22
	v_pk_add_f32 v[32:33], v[34:35], v[32:33]
	v_mov_b32_e32 v34, v27
	v_mov_b32_e32 v35, v23
	v_pk_add_f32 v[32:33], v[34:35], v[32:33]
	global_load_dwordx4 v[42:45], v[54:55], off
	global_load_dwordx4 v[46:49], v[56:57], off
	v_add_f32_e32 v32, v36, v32
	v_add_f32_e32 v32, v32, v33
	v_mov_b32_e32 v33, v32
	s_nop 1
	v_permlane32_swap_b32_e32 v33, v32
	s_waitcnt lgkmcnt(0)
	v_add_f32_e32 v32, v32, v33
	v_mov_b32_e32 v33, v32
	s_nop 1
	v_permlane16_swap_b32_e32 v33, v32
	s_waitcnt lgkmcnt(0)
	v_add_f32_e32 v32, v32, v33
	s_nop 1
	v_mov_b32_dpp v33, v32 row_ror:8 row_mask:0xf bank_mask:0xf
	s_waitcnt lgkmcnt(0)
	v_add_f32_e32 v32, v32, v33
	s_nop 1
	v_mov_b32_dpp v33, v32 row_ror:4 row_mask:0xf bank_mask:0xf
	s_waitcnt lgkmcnt(0)
	v_add_f32_e32 v32, v32, v33
	s_nop 1
	v_mov_b32_dpp v33, v32 row_ror:2 row_mask:0xf bank_mask:0xf
	s_waitcnt lgkmcnt(0)
	v_add_f32_e32 v32, v32, v33
	s_nop 1
	v_mov_b32_dpp v33, v32 row_ror:1 row_mask:0xf bank_mask:0xf
	s_waitcnt lgkmcnt(0)
	v_add_f32_e32 v32, v32, v33
	v_mul_f32_e32 v32, 0x3a800000, v32
	v_pk_add_f32 v[16:17], v[16:17], v[32:33] op_sel_hi:[1,0] neg_lo:[0,1] neg_hi:[0,1]
	v_pk_add_f32 v[40:41], v[28:29], v[32:33] op_sel_hi:[1,0] neg_lo:[0,1] neg_hi:[0,1]
	v_pk_add_f32 v[38:39], v[30:31], v[32:33] op_sel_hi:[1,0] neg_lo:[0,1] neg_hi:[0,1]
	v_pk_add_f32 v[34:35], v[24:25], v[32:33] op_sel_hi:[1,0] neg_lo:[0,1] neg_hi:[0,1]
	v_pk_add_f32 v[36:37], v[26:27], v[32:33] op_sel_hi:[1,0] neg_lo:[0,1] neg_hi:[0,1]
	v_pk_add_f32 v[24:25], v[20:21], v[32:33] op_sel_hi:[1,0] neg_lo:[0,1] neg_hi:[0,1]
	v_pk_add_f32 v[22:23], v[22:23], v[32:33] op_sel_hi:[1,0] neg_lo:[0,1] neg_hi:[0,1]
	v_pk_add_f32 v[18:19], v[18:19], v[32:33] op_sel_hi:[1,0] neg_lo:[0,1] neg_hi:[0,1]
	v_pk_mul_f32 v[32:33], v[16:17], v[16:17]
	v_pk_mul_f32 v[60:61], v[18:19], v[18:19]
	v_add_f32_e32 v32, v32, v33
	v_add_f32_e32 v32, v60, v32
	v_pk_mul_f32 v[28:29], v[40:41], v[40:41]
	v_add_f32_e32 v32, v61, v32
	v_add_f32_e32 v28, v28, v32
	v_pk_mul_f32 v[30:31], v[38:39], v[38:39]
	v_add_f32_e32 v28, v29, v28
	v_add_f32_e32 v28, v30, v28
	v_pk_mul_f32 v[50:51], v[34:35], v[34:35]
	v_add_f32_e32 v28, v31, v28
	v_add_f32_e32 v28, v50, v28
	v_pk_mul_f32 v[26:27], v[36:37], v[36:37]
	v_add_f32_e32 v28, v51, v28
	v_add_f32_e32 v26, v26, v28
	v_pk_mul_f32 v[20:21], v[24:25], v[24:25]
	v_add_f32_e32 v26, v27, v26
	v_add_f32_e32 v20, v20, v26
	v_pk_mul_f32 v[58:59], v[22:23], v[22:23]
	v_add_f32_e32 v20, v21, v20
	v_add_f32_e32 v20, v58, v20
	v_add_f32_e32 v20, v59, v20
	v_mov_b32_e32 v21, v20
	s_nop 1
	v_permlane32_swap_b32_e32 v21, v20
	s_waitcnt lgkmcnt(0)
	v_add_f32_e32 v20, v20, v21
	v_mov_b32_e32 v21, v20
	s_nop 1
	v_permlane16_swap_b32_e32 v21, v20
	s_waitcnt lgkmcnt(0)
	v_add_f32_e32 v20, v20, v21
	s_nop 1
	v_mov_b32_dpp v21, v20 row_ror:8 row_mask:0xf bank_mask:0xf
	s_waitcnt lgkmcnt(0)
	v_add_f32_e32 v26, v20, v21
	s_nop 1
	v_mov_b32_dpp v27, v26 row_ror:4 row_mask:0xf bank_mask:0xf
	v_lshl_add_u64 v[20:21], s[10:11], 2, v[64:65]
	v_alignbit_b32 v31, v21, v20, 13
	v_lshlrev_b64 v[28:29], 12, v[20:21]
	v_lshlrev_b64 v[20:21], 11, v[20:21]
	s_waitcnt lgkmcnt(0)
	v_add_f32_e32 v27, v26, v27
	s_nop 1
	v_mov_b32_dpp v30, v27 row_ror:2 row_mask:0xf bank_mask:0xf
	v_mov_b32_e32 v26, v193
	v_lshl_add_u64 v[28:29], s[92:93], 0, v[28:29]
	v_lshl_add_u64 v[20:21], s[96:97], 0, v[20:21]
	s_waitcnt lgkmcnt(0)
	v_add_f32_e32 v30, v27, v30
	s_nop 1
	v_mov_b32_dpp v32, v30 row_ror:1 row_mask:0xf bank_mask:0xf
	v_mul_lo_u32 v27, v31, s6
	v_ashrrev_i64 v[26:27], 30, v[26:27]
	s_waitcnt lgkmcnt(0)
	v_add_f32_e32 v30, v30, v32
	v_fmamk_f32 v30, v30, 0x3a800000, v220
	v_mul_f32_e32 v31, 0x4b800000, v30
	v_cmp_gt_f32_e32 vcc, s39, v30
	s_nop 1
	v_cndmask_b32_e32 v30, v30, v31, vcc
	v_rsq_f32_e32 v32, v30
	v_lshl_add_u64 v[30:31], v[28:29], 0, v[192:193]
	v_lshl_add_u64 v[28:29], s[16:17], 0, v[26:27]
	v_lshl_add_u64 v[26:27], s[66:67], 0, v[26:27]
	v_mul_f32_e32 v33, 0x45800000, v32
	v_cndmask_b32_e32 v32, v32, v33, vcc
	v_pk_mul_f32 v[16:17], v[16:17], v[32:33] op_sel_hi:[1,0]
	v_pk_mul_f32 v[18:19], v[18:19], v[32:33] op_sel_hi:[1,0]
	s_waitcnt vmcnt(0)
	v_pk_fma_f32 v[16:17], v[42:43], v[16:17], v[46:47]
	v_pk_fma_f32 v[18:19], v[44:45], v[18:19], v[48:49]
	s_and_b64 vcc, exec, s[0:1]
	global_store_dwordx4 v[30:31], v[16:19], off
	s_cbranch_vccnz .LBB0_240
	v_lshl_add_u64 v[42:43], v[28:29], 0, v[192:193]
	global_load_dwordx4 v[42:45], v[42:43], off
	v_lshl_add_u64 v[46:47], v[26:27], 0, v[192:193]
	global_load_dwordx4 v[46:49], v[46:47], off
	v_mov_b32_e32 v53, v193
	s_waitcnt vmcnt(1)
	v_pk_add_f32 v[42:43], v[42:43], 1.0 op_sel_hi:[1,0]
	s_waitcnt vmcnt(0)
	v_pk_fma_f32 v[16:17], v[16:17], v[42:43], v[46:47]
	v_pk_add_f32 v[42:43], v[44:45], 1.0 op_sel_hi:[1,0]
	v_cvt_pk_bf16_f32 v16, v16, v17
	v_pk_fma_f32 v[18:19], v[18:19], v[42:43], v[48:49]
	s_nop 0
	v_cvt_pk_bf16_f32 v17, v18, v19
	v_lshl_add_u64 v[18:19], v[20:21], 0, v[52:53]
	global_store_dwordx2 v[18:19], v[16:17], off

; DI unsigned pack2(float a, float b) { const hwf32x2 f = {a, b}; return __builtin_bit_cast(unsigned, __builtin_convertvector(f, hwbf16x2)); }
; template <int GRP>
; DI void ln_items(float* X, const float* gam, const float* bet, bf16_t* u2, const float* sc, const float* sh, int item0) {
;     ...
;   for (int g = 0; g < GRP; ++g) {
;     const size_t tok = (size_t)(item0 + g) * 4 + wave;
;     const int b = (int)(tok >> 13);
;     float s = 0.f;
; #pragma unroll
;     for (int j = 0; j < 4; ++j) s += v[g][j][0] + v[g][j][1] + v[g][j][2] + v[g][j][3];
; #pragma unroll
;     for (int off = 32; off >= 1; off >>= 1) s += __shfl_xor(s, off);
;     const float mu = s * (1.f / 1024.f);
;     float q = 0.f;
; #pragma unroll
;     for (int j = 0; j < 4; ++j)
; #pragma unroll
;       for (int e = 0; e < 4; ++e) { const float d = v[g][j][e] - mu; q += d * d; }
; #pragma unroll
;     for (int off = 32; off >= 1; off >>= 1) q += __shfl_xor(q, off);
;     const float rstd = rsqrtf(q * (1.f / 1024.f) + 1e-5f);
; #pragma unroll
;     for (int j = 0; j < 4; ++j) {
;       const int col = j * 256 + lane * 4;
;       const f32x4 gg = *(const f32x4*)(gam + col), be = *(const f32x4*)(bet + col);
;       f32x4 y;
; #pragma unroll
;       for (int e = 0; e < 4; ++e) y[e] = (v[g][j][e] - mu) * rstd * gg[e] + be[e];
;       *(f32x4*)(X + tok * 1024 + col) = y;
;       if (u2) {
;         const f32x4 s4 = *(const f32x4*)(sc + b * 6144 + col), h4 = *(const f32x4*)(sh + b * 6144 + col);
;         uint2 o;
;         o.x = pack2(y[0] * (1.f + s4[0]) + h4[0], y[1] * (1.f + s4[1]) + h4[1]);
;         o.y = pack2(y[2] * (1.f + s4[2]) + h4[2], y[3] * (1.f + s4[3]) + h4[3]);
;         *(uint2*)(u2 + tok * 1024 + col) = o;
;       }
;     }
.LBB0_246:
	s_nop 0
	v_mov_b32_e32 v16, v0
	v_mov_b32_e32 v17, v12
	v_mov_b32_e32 v18, v1
	v_mov_b32_e32 v19, v13
	v_pk_add_f32 v[16:17], v[16:17], v[18:19]
	v_mov_b32_e32 v18, v2
	v_mov_b32_e32 v19, v14
	v_pk_add_f32 v[16:17], v[18:19], v[16:17]
	v_mov_b32_e32 v18, v3
	v_mov_b32_e32 v19, v15
	v_pk_add_f32 v[16:17], v[18:19], v[16:17]
	v_mov_b32_e32 v18, v9
	v_add_f32_e32 v16, 0, v16
	v_add_f32_e32 v20, v16, v17
	v_mov_b32_e32 v16, v8
	v_mov_b32_e32 v17, v4
	v_mov_b32_e32 v19, v5
	v_pk_add_f32 v[16:17], v[16:17], v[18:19]
	v_mov_b32_e32 v18, v10
	v_mov_b32_e32 v19, v6
	v_pk_add_f32 v[16:17], v[18:19], v[16:17]
	v_mov_b32_e32 v18, v11
	v_mov_b32_e32 v19, v7
	v_pk_add_f32 v[16:17], v[18:19], v[16:17]
	global_load_dwordx4 v[26:29], v[54:55], off
	global_load_dwordx4 v[30:33], v[56:57], off
	v_add_f32_e32 v16, v20, v16
	v_add_f32_e32 v16, v16, v17
	v_mov_b32_e32 v17, v16
	s_nop 1
	v_permlane32_swap_b32_e32 v17, v16
	s_waitcnt lgkmcnt(0)
	v_add_f32_e32 v16, v16, v17
	v_mov_b32_e32 v17, v16
	s_nop 1
	v_permlane16_swap_b32_e32 v17, v16
	s_waitcnt lgkmcnt(0)
	v_add_f32_e32 v16, v16, v17
	s_nop 1
	v_mov_b32_dpp v17, v16 row_ror:8 row_mask:0xf bank_mask:0xf
	s_waitcnt lgkmcnt(0)
	v_add_f32_e32 v16, v16, v17
	s_nop 1
	v_mov_b32_dpp v17, v16 row_ror:4 row_mask:0xf bank_mask:0xf
	s_waitcnt lgkmcnt(0)
	v_add_f32_e32 v16, v16, v17
	s_nop 1
	v_mov_b32_dpp v17, v16 row_ror:2 row_mask:0xf bank_mask:0xf
	s_waitcnt lgkmcnt(0)
	v_add_f32_e32 v16, v16, v17
	s_nop 1
	v_mov_b32_dpp v17, v16 row_ror:1 row_mask:0xf bank_mask:0xf
	s_waitcnt lgkmcnt(0)
	v_add_f32_e32 v16, v16, v17
	v_mul_f32_e32 v16, 0x3a800000, v16
	v_pk_add_f32 v[0:1], v[0:1], v[16:17] op_sel_hi:[1,0] neg_lo:[0,1] neg_hi:[0,1]
	v_pk_add_f32 v[24:25], v[12:13], v[16:17] op_sel_hi:[1,0] neg_lo:[0,1] neg_hi:[0,1]
	v_pk_add_f32 v[22:23], v[14:15], v[16:17] op_sel_hi:[1,0] neg_lo:[0,1] neg_hi:[0,1]
	v_pk_add_f32 v[18:19], v[8:9], v[16:17] op_sel_hi:[1,0] neg_lo:[0,1] neg_hi:[0,1]
	v_pk_add_f32 v[20:21], v[10:11], v[16:17] op_sel_hi:[1,0] neg_lo:[0,1] neg_hi:[0,1]
	v_pk_add_f32 v[8:9], v[4:5], v[16:17] op_sel_hi:[1,0] neg_lo:[0,1] neg_hi:[0,1]
	v_pk_add_f32 v[6:7], v[6:7], v[16:17] op_sel_hi:[1,0] neg_lo:[0,1] neg_hi:[0,1]
	v_pk_add_f32 v[2:3], v[2:3], v[16:17] op_sel_hi:[1,0] neg_lo:[0,1] neg_hi:[0,1]
	v_pk_mul_f32 v[16:17], v[0:1], v[0:1]
	v_pk_mul_f32 v[38:39], v[2:3], v[2:3]
	v_add_f32_e32 v16, v16, v17
	v_add_f32_e32 v16, v38, v16
	v_pk_mul_f32 v[12:13], v[24:25], v[24:25]
	v_add_f32_e32 v16, v39, v16
	v_add_f32_e32 v12, v12, v16
	v_pk_mul_f32 v[14:15], v[22:23], v[22:23]
	v_add_f32_e32 v12, v13, v12
	v_add_f32_e32 v12, v14, v12
	v_pk_mul_f32 v[34:35], v[18:19], v[18:19]
	v_add_f32_e32 v12, v15, v12
	v_add_f32_e32 v12, v34, v12
	v_pk_mul_f32 v[10:11], v[20:21], v[20:21]
	v_add_f32_e32 v12, v35, v12
	v_add_f32_e32 v10, v10, v12
	v_pk_mul_f32 v[4:5], v[8:9], v[8:9]
	v_add_f32_e32 v10, v11, v10
	v_add_f32_e32 v4, v4, v10
	v_pk_mul_f32 v[36:37], v[6:7], v[6:7]
	v_add_f32_e32 v4, v5, v4
	v_add_f32_e32 v4, v36, v4
	v_add_f32_e32 v4, v37, v4
	v_mov_b32_e32 v5, v4
	s_nop 1
	v_permlane32_swap_b32_e32 v5, v4
	s_waitcnt lgkmcnt(0)
	v_add_f32_e32 v4, v4, v5
	v_mov_b32_e32 v5, v4
	s_nop 1
	v_permlane16_swap_b32_e32 v5, v4
	s_waitcnt lgkmcnt(0)
	v_add_f32_e32 v4, v4, v5
	s_nop 1
	v_mov_b32_dpp v5, v4 row_ror:8 row_mask:0xf bank_mask:0xf
	s_waitcnt lgkmcnt(0)
	v_add_f32_e32 v10, v4, v5
	s_nop 1
	v_mov_b32_dpp v11, v10 row_ror:4 row_mask:0xf bank_mask:0xf
	v_lshl_add_u64 v[4:5], s[8:9], 2, v[64:65]
	v_alignbit_b32 v15, v5, v4, 13
	v_lshlrev_b64 v[12:13], 12, v[4:5]
	v_lshlrev_b64 v[4:5], 11, v[4:5]
	s_waitcnt lgkmcnt(0)
	v_add_f32_e32 v11, v10, v11
	s_nop 1
	v_mov_b32_dpp v14, v11 row_ror:2 row_mask:0xf bank_mask:0xf
	v_mov_b32_e32 v10, v193
	v_lshl_add_u64 v[12:13], s[92:93], 0, v[12:13]
	v_lshl_add_u64 v[4:5], s[96:97], 0, v[4:5]
	s_waitcnt lgkmcnt(0)
	v_add_f32_e32 v14, v11, v14
	s_nop 1
	v_mov_b32_dpp v16, v14 row_ror:1 row_mask:0xf bank_mask:0xf
	v_mul_lo_u32 v11, v15, s6
	v_ashrrev_i64 v[10:11], 30, v[10:11]
	s_waitcnt lgkmcnt(0)
	v_add_f32_e32 v14, v14, v16
	v_fmamk_f32 v14, v14, 0x3a800000, v220
	v_mul_f32_e32 v15, 0x4b800000, v14
	v_cmp_gt_f32_e32 vcc, s39, v14
	s_nop 1
	v_cndmask_b32_e32 v14, v14, v15, vcc
	v_rsq_f32_e32 v16, v14
	v_lshl_add_u64 v[14:15], v[12:13], 0, v[192:193]
	v_lshl_add_u64 v[12:13], s[16:17], 0, v[10:11]
	v_lshl_add_u64 v[10:11], s[66:67], 0, v[10:11]
	v_mul_f32_e32 v17, 0x45800000, v16
	v_cndmask_b32_e32 v16, v16, v17, vcc
	v_pk_mul_f32 v[0:1], v[0:1], v[16:17] op_sel_hi:[1,0]
	v_pk_mul_f32 v[2:3], v[2:3], v[16:17] op_sel_hi:[1,0]
	s_waitcnt vmcnt(0)
	v_pk_fma_f32 v[0:1], v[26:27], v[0:1], v[30:31]
	v_pk_fma_f32 v[2:3], v[28:29], v[2:3], v[32:33]
	s_and_b64 vcc, exec, s[0:1]
	global_store_dwordx4 v[14:15], v[0:3], off
	s_cbranch_vccnz .LBB0_248
	v_lshl_add_u64 v[26:27], v[12:13], 0, v[192:193]
	global_load_dwordx4 v[26:29], v[26:27], off
	v_lshl_add_u64 v[30:31], v[10:11], 0, v[192:193]
	global_load_dwordx4 v[30:33], v[30:31], off
	v_mov_b32_e32 v53, v193
	s_waitcnt vmcnt(1)
	v_pk_add_f32 v[26:27], v[26:27], 1.0 op_sel_hi:[1,0]
	s_waitcnt vmcnt(0)
	v_pk_fma_f32 v[0:1], v[0:1], v[26:27], v[30:31]
	v_pk_add_f32 v[26:27], v[28:29], 1.0 op_sel_hi:[1,0]
	v_cvt_pk_bf16_f32 v0, v0, v1
	v_pk_fma_f32 v[2:3], v[2:3], v[26:27], v[32:33]
	s_nop 0
	v_cvt_pk_bf16_f32 v1, v2, v3
	v_lshl_add_u64 v[2:3], v[4:5], 0, v[52:53]
	global_store_dwordx2 v[2:3], v[0:1], off
